# v15 + closing s_barrier of each K-loop compute segment moved up by one MFMA (hand-off overlaps the last MFMA)
# speedup vs baseline: 1.0106x; 1.0065x over previous
.LBB0_252:
	s_add_u32 s12, s54, 0xfff00080
	s_addc_u32 s13, s55, -1
	s_add_i32 s95, 0, 0x10000
	s_cmp_eq_u32 s94, 60
	s_cselect_b32 s65, s47, s13
	s_cselect_b32 s64, s66, s12
	s_cselect_b32 s63, s45, s61
	s_cselect_b32 s62, vcc_lo, vcc_hi
	s_add_i32 s56, 0, 0x14000
	v_add_u32_e32 v142, s95, v144
	ds_read_b128 v[148:151], v142
	ds_read_b128 v[152:155], v142 offset:1024
	ds_read_b128 v[156:159], v142 offset:2048
	ds_read_b128 v[160:163], v142 offset:3072
	v_add_u32_e32 v142, s56, v144
	ds_read_b128 v[164:167], v142
	ds_read_b128 v[168:171], v142 offset:1024
	ds_read_b128 v[172:175], v142 offset:2048
	ds_read_b128 v[176:179], v142 offset:3072
	ds_read_b128 v[180:183], v146
	ds_read_b128 v[184:187], v146 offset:1024
	ds_read_b128 v[210:213], v146 offset:2048
	ds_read_b128 v[214:217], v146 offset:3072
	ds_read_b128 v[218:221], v146 offset:4096
	ds_read_b128 v[222:225], v146 offset:5120
	ds_read_b128 v[226:229], v146 offset:6144
	ds_read_b128 v[230:233], v146 offset:7168
	s_add_i32 m0, s53, 0xc000
	s_nop 0
	global_load_lds_dwordx4 v136, s[54:55]
	s_add_i32 m0, s53, 0xe000
	s_nop 0
	global_load_lds_dwordx4 v138, s[54:55]
	s_waitcnt vmcnt(8)
	s_waitcnt lgkmcnt(0)
	s_barrier
	s_setprio 1
	s_waitcnt lgkmcnt(0)
	v_mfma_f32_16x16x32_bf16 v[126:129], v[148:151], v[180:183], v[126:129]
	v_mfma_f32_16x16x32_bf16 v[126:129], v[152:155], v[184:187], v[126:129]
	v_mfma_f32_16x16x32_bf16 v[114:117], v[152:155], v[214:217], v[114:117]
	v_mfma_f32_16x16x32_bf16 v[114:117], v[148:151], v[210:213], v[114:117]
	v_mfma_f32_16x16x32_bf16 v[98:101], v[148:151], v[218:221], v[98:101]
	v_mfma_f32_16x16x32_bf16 v[98:101], v[152:155], v[222:225], v[98:101]
	v_mfma_f32_16x16x32_bf16 v[82:85], v[152:155], v[230:233], v[82:85]
	v_mfma_f32_16x16x32_bf16 v[82:85], v[148:151], v[226:229], v[82:85]
	v_mfma_f32_16x16x32_bf16 v[74:77], v[156:159], v[226:229], v[74:77]
	v_mfma_f32_16x16x32_bf16 v[74:77], v[160:163], v[230:233], v[74:77]
	v_mfma_f32_16x16x32_bf16 v[90:93], v[160:163], v[222:225], v[90:93]
	v_mfma_f32_16x16x32_bf16 v[90:93], v[156:159], v[218:221], v[90:93]
	v_mfma_f32_16x16x32_bf16 v[106:109], v[156:159], v[210:213], v[106:109]
	v_mfma_f32_16x16x32_bf16 v[106:109], v[160:163], v[214:217], v[106:109]
	v_mfma_f32_16x16x32_bf16 v[122:125], v[160:163], v[184:187], v[122:125]
	v_mfma_f32_16x16x32_bf16 v[122:125], v[156:159], v[180:183], v[122:125]
	v_mfma_f32_16x16x32_bf16 v[110:113], v[172:175], v[180:183], v[110:113]
	v_mfma_f32_16x16x32_bf16 v[110:113], v[176:179], v[184:187], v[110:113]
	v_mfma_f32_16x16x32_bf16 v[94:97], v[176:179], v[214:217], v[94:97]
	v_mfma_f32_16x16x32_bf16 v[94:97], v[172:175], v[210:213], v[94:97]
	v_mfma_f32_16x16x32_bf16 v[78:81], v[172:175], v[218:221], v[78:81]
	v_mfma_f32_16x16x32_bf16 v[78:81], v[176:179], v[222:225], v[78:81]
	v_mfma_f32_16x16x32_bf16 v[66:69], v[176:179], v[230:233], v[66:69]
	v_mfma_f32_16x16x32_bf16 v[66:69], v[172:175], v[226:229], v[66:69]
	v_mfma_f32_16x16x32_bf16 v[70:73], v[164:167], v[226:229], v[70:73]
	v_mfma_f32_16x16x32_bf16 v[70:73], v[168:171], v[230:233], v[70:73]
	v_mfma_f32_16x16x32_bf16 v[86:89], v[168:171], v[222:225], v[86:89]
	v_mfma_f32_16x16x32_bf16 v[86:89], v[164:167], v[218:221], v[86:89]
	v_mfma_f32_16x16x32_bf16 v[102:105], v[164:167], v[210:213], v[102:105]
	v_mfma_f32_16x16x32_bf16 v[102:105], v[168:171], v[214:217], v[102:105]
	v_mfma_f32_16x16x32_bf16 v[118:121], v[168:171], v[184:187], v[118:121]
	s_barrier
	v_mfma_f32_16x16x32_bf16 v[118:121], v[164:167], v[180:183], v[118:121]
	s_setprio 0
	s_add_i32 s12, s95, s82
	ds_read_b128 v[180:183], v146 offset:16384
	ds_read_b128 v[184:187], v146 offset:17408
	ds_read_b128 v[210:213], v146 offset:18432
	ds_read_b128 v[214:217], v146 offset:19456
	ds_read_b128 v[218:221], v146 offset:20480
	ds_read_b128 v[222:225], v146 offset:21504
	ds_read_b128 v[226:229], v146 offset:22528
	ds_read_b128 v[230:233], v146 offset:23552
	s_mov_b32 m0, s12
	s_nop 0
	global_load_lds_dwordx4 v190, s[62:63]
	s_add_i32 m0, s12, 0x2000
	s_add_u32 s12, s62, 0x100000
	s_addc_u32 s13, s63, 0
	s_add_i32 s56, s56, s82
	global_load_lds_dwordx4 v134, s[62:63]
	s_mov_b32 m0, s56
	s_nop 0
	global_load_lds_dwordx4 v190, s[12:13]
	s_add_i32 m0, s56, 0x2000
	s_nop 0
	global_load_lds_dwordx4 v134, s[12:13]
	s_mov_b32 m0, s53
	s_nop 0
	global_load_lds_dwordx4 v130, s[64:65]
	s_mov_b32 m0, s84
	s_nop 0
	global_load_lds_dwordx4 v132, s[64:65]
	s_waitcnt vmcnt(8)
	s_waitcnt lgkmcnt(0)
	s_barrier
	s_setprio 1
	s_waitcnt lgkmcnt(0)
	v_mfma_f32_16x16x32_bf16 v[62:65], v[148:151], v[180:183], v[62:65]
	v_mfma_f32_16x16x32_bf16 v[62:65], v[152:155], v[184:187], v[62:65]
	v_mfma_f32_16x16x32_bf16 v[50:53], v[152:155], v[214:217], v[50:53]
	v_mfma_f32_16x16x32_bf16 v[50:53], v[148:151], v[210:213], v[50:53]
	v_mfma_f32_16x16x32_bf16 v[34:37], v[148:151], v[218:221], v[34:37]
	v_mfma_f32_16x16x32_bf16 v[34:37], v[152:155], v[222:225], v[34:37]
	v_mfma_f32_16x16x32_bf16 v[18:21], v[152:155], v[230:233], v[18:21]
	v_mfma_f32_16x16x32_bf16 v[18:21], v[148:151], v[226:229], v[18:21]
	v_mfma_f32_16x16x32_bf16 v[10:13], v[156:159], v[226:229], v[10:13]
	v_mfma_f32_16x16x32_bf16 v[10:13], v[160:163], v[230:233], v[10:13]
	v_mfma_f32_16x16x32_bf16 v[26:29], v[160:163], v[222:225], v[26:29]
	v_mfma_f32_16x16x32_bf16 v[26:29], v[156:159], v[218:221], v[26:29]
	v_mfma_f32_16x16x32_bf16 v[42:45], v[156:159], v[210:213], v[42:45]
	v_mfma_f32_16x16x32_bf16 v[42:45], v[160:163], v[214:217], v[42:45]
	v_mfma_f32_16x16x32_bf16 v[58:61], v[160:163], v[184:187], v[58:61]
	v_mfma_f32_16x16x32_bf16 v[58:61], v[156:159], v[180:183], v[58:61]
	v_mfma_f32_16x16x32_bf16 v[46:49], v[172:175], v[180:183], v[46:49]
	v_mfma_f32_16x16x32_bf16 v[46:49], v[176:179], v[184:187], v[46:49]
	v_mfma_f32_16x16x32_bf16 v[30:33], v[176:179], v[214:217], v[30:33]
	v_mfma_f32_16x16x32_bf16 v[30:33], v[172:175], v[210:213], v[30:33]
	v_mfma_f32_16x16x32_bf16 v[14:17], v[172:175], v[218:221], v[14:17]
	v_mfma_f32_16x16x32_bf16 v[14:17], v[176:179], v[222:225], v[14:17]
	v_mfma_f32_16x16x32_bf16 v[2:5], v[176:179], v[230:233], v[2:5]
	v_mfma_f32_16x16x32_bf16 v[2:5], v[172:175], v[226:229], v[2:5]
	v_mfma_f32_16x16x32_bf16 v[6:9], v[164:167], v[226:229], v[6:9]
	v_mfma_f32_16x16x32_bf16 v[6:9], v[168:171], v[230:233], v[6:9]
	v_mfma_f32_16x16x32_bf16 v[22:25], v[168:171], v[222:225], v[22:25]
	v_mfma_f32_16x16x32_bf16 v[22:25], v[164:167], v[218:221], v[22:25]
	v_mfma_f32_16x16x32_bf16 v[38:41], v[164:167], v[210:213], v[38:41]
	v_mfma_f32_16x16x32_bf16 v[38:41], v[168:171], v[214:217], v[38:41]
	v_mfma_f32_16x16x32_bf16 v[54:57], v[168:171], v[184:187], v[54:57]
	s_barrier
	v_mfma_f32_16x16x32_bf16 v[54:57], v[164:167], v[180:183], v[54:57]
	s_setprio 0
	s_add_i32 s56, 0, 0x18000
	s_add_i32 s95, 0, 0x1c000
	s_add_u32 s12, s64, 0x100000
	s_addc_u32 s13, s65, 0
	v_add_u32_e32 v147, s56, v144
	ds_read_b128 v[148:151], v147
	ds_read_b128 v[152:155], v147 offset:1024
	ds_read_b128 v[156:159], v147 offset:2048
	ds_read_b128 v[160:163], v147 offset:3072
	v_add_u32_e32 v147, s95, v144
	ds_read_b128 v[164:167], v147
	ds_read_b128 v[168:171], v147 offset:1024
	ds_read_b128 v[172:175], v147 offset:2048
	ds_read_b128 v[176:179], v147 offset:3072
	ds_read_b128 v[180:183], v146 offset:32768
	ds_read_b128 v[184:187], v146 offset:33792
	ds_read_b128 v[210:213], v146 offset:34816
	ds_read_b128 v[214:217], v146 offset:35840
	ds_read_b128 v[218:221], v146 offset:36864
	ds_read_b128 v[222:225], v146 offset:37888
	ds_read_b128 v[226:229], v146 offset:38912
	ds_read_b128 v[230:233], v146 offset:39936
	s_mov_b32 m0, s85
	s_nop 0
	global_load_lds_dwordx4 v130, s[12:13]
	s_mov_b32 m0, s86
	s_nop 0
	global_load_lds_dwordx4 v132, s[12:13]
	s_waitcnt vmcnt(8)
	s_waitcnt lgkmcnt(0)
	s_barrier
	s_setprio 1
	s_waitcnt lgkmcnt(0)
	v_mfma_f32_16x16x32_bf16 v[126:129], v[148:151], v[180:183], v[126:129]
	v_mfma_f32_16x16x32_bf16 v[126:129], v[152:155], v[184:187], v[126:129]
	v_mfma_f32_16x16x32_bf16 v[114:117], v[152:155], v[214:217], v[114:117]
	v_mfma_f32_16x16x32_bf16 v[114:117], v[148:151], v[210:213], v[114:117]
	v_mfma_f32_16x16x32_bf16 v[98:101], v[148:151], v[218:221], v[98:101]
	v_mfma_f32_16x16x32_bf16 v[98:101], v[152:155], v[222:225], v[98:101]
	v_mfma_f32_16x16x32_bf16 v[82:85], v[152:155], v[230:233], v[82:85]
	v_mfma_f32_16x16x32_bf16 v[82:85], v[148:151], v[226:229], v[82:85]
	v_mfma_f32_16x16x32_bf16 v[74:77], v[156:159], v[226:229], v[74:77]
	v_mfma_f32_16x16x32_bf16 v[74:77], v[160:163], v[230:233], v[74:77]
	v_mfma_f32_16x16x32_bf16 v[90:93], v[160:163], v[222:225], v[90:93]
	v_mfma_f32_16x16x32_bf16 v[90:93], v[156:159], v[218:221], v[90:93]
	v_mfma_f32_16x16x32_bf16 v[106:109], v[156:159], v[210:213], v[106:109]
	v_mfma_f32_16x16x32_bf16 v[106:109], v[160:163], v[214:217], v[106:109]
	v_mfma_f32_16x16x32_bf16 v[122:125], v[160:163], v[184:187], v[122:125]
	v_mfma_f32_16x16x32_bf16 v[122:125], v[156:159], v[180:183], v[122:125]
	v_mfma_f32_16x16x32_bf16 v[110:113], v[172:175], v[180:183], v[110:113]
	v_mfma_f32_16x16x32_bf16 v[110:113], v[176:179], v[184:187], v[110:113]
	v_mfma_f32_16x16x32_bf16 v[94:97], v[176:179], v[214:217], v[94:97]
	v_mfma_f32_16x16x32_bf16 v[94:97], v[172:175], v[210:213], v[94:97]
	v_mfma_f32_16x16x32_bf16 v[78:81], v[172:175], v[218:221], v[78:81]
	v_mfma_f32_16x16x32_bf16 v[78:81], v[176:179], v[222:225], v[78:81]
	v_mfma_f32_16x16x32_bf16 v[66:69], v[176:179], v[230:233], v[66:69]
	v_mfma_f32_16x16x32_bf16 v[66:69], v[172:175], v[226:229], v[66:69]
	v_mfma_f32_16x16x32_bf16 v[70:73], v[164:167], v[226:229], v[70:73]
	v_mfma_f32_16x16x32_bf16 v[70:73], v[168:171], v[230:233], v[70:73]
	v_mfma_f32_16x16x32_bf16 v[86:89], v[168:171], v[222:225], v[86:89]
	v_mfma_f32_16x16x32_bf16 v[86:89], v[164:167], v[218:221], v[86:89]
	v_mfma_f32_16x16x32_bf16 v[102:105], v[164:167], v[210:213], v[102:105]
	v_mfma_f32_16x16x32_bf16 v[102:105], v[168:171], v[214:217], v[102:105]
	v_mfma_f32_16x16x32_bf16 v[118:121], v[168:171], v[184:187], v[118:121]
	s_barrier
	v_mfma_f32_16x16x32_bf16 v[118:121], v[164:167], v[180:183], v[118:121]
	s_setprio 0
	s_add_i32 s12, s56, s82
	ds_read_b128 v[180:183], v146 offset:49152
	ds_read_b128 v[184:187], v146 offset:50176
	ds_read_b128 v[210:213], v146 offset:51200
	ds_read_b128 v[214:217], v146 offset:52224
	ds_read_b128 v[218:221], v146 offset:53248
	ds_read_b128 v[222:225], v146 offset:54272
	ds_read_b128 v[226:229], v146 offset:55296
	ds_read_b128 v[230:233], v146 offset:56320
	s_mov_b32 m0, s12
	s_nop 0
	global_load_lds_dwordx4 v234, s[62:63]
	s_add_i32 m0, s12, 0x2000
	s_add_u32 s12, s62, 0x100080
	s_addc_u32 s13, s63, 0
	s_add_i32 s56, s95, s82
	global_load_lds_dwordx4 v189, s[62:63]
	s_mov_b32 m0, s56
	s_nop 0
	global_load_lds_dwordx4 v190, s[12:13]
	s_add_i32 m0, s56, 0x2000
	s_nop 0
	global_load_lds_dwordx4 v134, s[12:13]
	s_mov_b32 m0, s90
	s_nop 0
	global_load_lds_dwordx4 v143, s[64:65]
	s_mov_b32 m0, s97
	s_nop 0
	global_load_lds_dwordx4 v188, s[64:65]
	s_waitcnt vmcnt(8)
	s_waitcnt lgkmcnt(0)
	s_barrier
	s_setprio 1
	s_waitcnt lgkmcnt(0)
	v_mfma_f32_16x16x32_bf16 v[62:65], v[148:151], v[180:183], v[62:65]
	v_mfma_f32_16x16x32_bf16 v[62:65], v[152:155], v[184:187], v[62:65]
	v_mfma_f32_16x16x32_bf16 v[50:53], v[152:155], v[214:217], v[50:53]
	v_mfma_f32_16x16x32_bf16 v[50:53], v[148:151], v[210:213], v[50:53]
	v_mfma_f32_16x16x32_bf16 v[34:37], v[148:151], v[218:221], v[34:37]
	v_mfma_f32_16x16x32_bf16 v[34:37], v[152:155], v[222:225], v[34:37]
	v_mfma_f32_16x16x32_bf16 v[18:21], v[152:155], v[230:233], v[18:21]
	v_mfma_f32_16x16x32_bf16 v[18:21], v[148:151], v[226:229], v[18:21]
	v_mfma_f32_16x16x32_bf16 v[10:13], v[156:159], v[226:229], v[10:13]
	v_mfma_f32_16x16x32_bf16 v[10:13], v[160:163], v[230:233], v[10:13]
	v_mfma_f32_16x16x32_bf16 v[26:29], v[160:163], v[222:225], v[26:29]
	v_mfma_f32_16x16x32_bf16 v[26:29], v[156:159], v[218:221], v[26:29]
	v_mfma_f32_16x16x32_bf16 v[42:45], v[156:159], v[210:213], v[42:45]
	v_mfma_f32_16x16x32_bf16 v[42:45], v[160:163], v[214:217], v[42:45]
	v_mfma_f32_16x16x32_bf16 v[58:61], v[160:163], v[184:187], v[58:61]
	v_mfma_f32_16x16x32_bf16 v[58:61], v[156:159], v[180:183], v[58:61]
	v_mfma_f32_16x16x32_bf16 v[46:49], v[172:175], v[180:183], v[46:49]
	v_mfma_f32_16x16x32_bf16 v[46:49], v[176:179], v[184:187], v[46:49]
	v_mfma_f32_16x16x32_bf16 v[30:33], v[176:179], v[214:217], v[30:33]
	v_mfma_f32_16x16x32_bf16 v[30:33], v[172:175], v[210:213], v[30:33]
	v_mfma_f32_16x16x32_bf16 v[14:17], v[172:175], v[218:221], v[14:17]
	v_mfma_f32_16x16x32_bf16 v[14:17], v[176:179], v[222:225], v[14:17]
	v_mfma_f32_16x16x32_bf16 v[2:5], v[176:179], v[230:233], v[2:5]
	v_mfma_f32_16x16x32_bf16 v[2:5], v[172:175], v[226:229], v[2:5]
	v_mfma_f32_16x16x32_bf16 v[6:9], v[164:167], v[226:229], v[6:9]
	v_mfma_f32_16x16x32_bf16 v[6:9], v[168:171], v[230:233], v[6:9]
	v_mfma_f32_16x16x32_bf16 v[22:25], v[168:171], v[222:225], v[22:25]
	v_mfma_f32_16x16x32_bf16 v[22:25], v[164:167], v[218:221], v[22:25]
	v_mfma_f32_16x16x32_bf16 v[38:41], v[164:167], v[210:213], v[38:41]
	v_mfma_f32_16x16x32_bf16 v[38:41], v[168:171], v[214:217], v[38:41]
	v_mfma_f32_16x16x32_bf16 v[54:57], v[168:171], v[184:187], v[54:57]
	s_barrier
	v_mfma_f32_16x16x32_bf16 v[54:57], v[164:167], v[180:183], v[54:57]
	s_setprio 0
	s_add_i32 s94, s94, 2
	s_add_u32 s54, s54, 0x100
	s_addc_u32 s55, s55, 0
	s_add_u32 vcc_hi, vcc_hi, 0x100
	s_addc_u32 s61, s61, 0
	s_cmp_gt_u32 s94, 61
	s_cbranch_scc0 .LBB0_252
	s_and_b64 vcc, exec, s[42:43]
	s_cbranch_vccz .LBB0_255
	s_barrier

.LBB0_692:
	s_add_u32 s12, s40, 0xfffc0080
	s_addc_u32 s13, s41, -1
	s_add_i32 s56, 0, 0x10000
	s_cmp_eq_u32 s74, 12
	s_cselect_b32 s63, s47, s13
	s_cselect_b32 s62, s71, s12
	s_cselect_b32 s55, s45, s61
	s_cselect_b32 s54, s72, s73
	s_add_i32 s75, 0, 0x14000
	v_add_u32_e32 v142, s56, v160
	v_add_u32_e32 v163, s75, v160
	ds_read_b128 v[130:133], v142
	ds_read_b128 v[134:137], v142 offset:1024
	ds_read_b128 v[138:141], v142 offset:2048
	ds_read_b128 v[142:145], v142 offset:3072
	ds_read_b128 v[156:159], v163
	ds_read_b128 v[164:167], v163 offset:1024
	ds_read_b128 v[168:171], v163 offset:2048
	ds_read_b128 v[172:175], v163 offset:3072
	ds_read_b128 v[176:179], v162
	ds_read_b128 v[180:183], v162 offset:1024
	ds_read_b128 v[184:187], v162 offset:2048
	ds_read_b128 v[210:213], v162 offset:3072
	ds_read_b128 v[214:217], v162 offset:4096
	ds_read_b128 v[218:221], v162 offset:5120
	ds_read_b128 v[222:225], v162 offset:6144
	ds_read_b128 v[226:229], v162 offset:7168
	s_add_i32 m0, s53, 0xc000
	s_nop 0
	global_load_lds_dwordx4 v152, s[40:41]
	s_add_i32 m0, s53, 0xe000
	s_nop 0
	global_load_lds_dwordx4 v154, s[40:41]
	s_waitcnt vmcnt(8)
	s_waitcnt lgkmcnt(0)
	s_barrier
	s_setprio 1
	s_waitcnt lgkmcnt(0)
	v_mfma_f32_16x16x32_bf16 v[126:129], v[130:133], v[176:179], v[126:129]
	v_mfma_f32_16x16x32_bf16 v[126:129], v[134:137], v[180:183], v[126:129]
	v_mfma_f32_16x16x32_bf16 v[114:117], v[134:137], v[210:213], v[114:117]
	v_mfma_f32_16x16x32_bf16 v[114:117], v[130:133], v[184:187], v[114:117]
	v_mfma_f32_16x16x32_bf16 v[98:101], v[130:133], v[214:217], v[98:101]
	v_mfma_f32_16x16x32_bf16 v[98:101], v[134:137], v[218:221], v[98:101]
	v_mfma_f32_16x16x32_bf16 v[82:85], v[134:137], v[226:229], v[82:85]
	v_mfma_f32_16x16x32_bf16 v[82:85], v[130:133], v[222:225], v[82:85]
	v_mfma_f32_16x16x32_bf16 v[74:77], v[138:141], v[222:225], v[74:77]
	v_mfma_f32_16x16x32_bf16 v[74:77], v[142:145], v[226:229], v[74:77]
	v_mfma_f32_16x16x32_bf16 v[90:93], v[142:145], v[218:221], v[90:93]
	v_mfma_f32_16x16x32_bf16 v[90:93], v[138:141], v[214:217], v[90:93]
	v_mfma_f32_16x16x32_bf16 v[106:109], v[138:141], v[184:187], v[106:109]
	v_mfma_f32_16x16x32_bf16 v[106:109], v[142:145], v[210:213], v[106:109]
	v_mfma_f32_16x16x32_bf16 v[122:125], v[142:145], v[180:183], v[122:125]
	v_mfma_f32_16x16x32_bf16 v[122:125], v[138:141], v[176:179], v[122:125]
	v_mfma_f32_16x16x32_bf16 v[110:113], v[168:171], v[176:179], v[110:113]
	v_mfma_f32_16x16x32_bf16 v[110:113], v[172:175], v[180:183], v[110:113]
	v_mfma_f32_16x16x32_bf16 v[94:97], v[172:175], v[210:213], v[94:97]
	v_mfma_f32_16x16x32_bf16 v[94:97], v[168:171], v[184:187], v[94:97]
	v_mfma_f32_16x16x32_bf16 v[78:81], v[168:171], v[214:217], v[78:81]
	v_mfma_f32_16x16x32_bf16 v[78:81], v[172:175], v[218:221], v[78:81]
	v_mfma_f32_16x16x32_bf16 v[66:69], v[172:175], v[226:229], v[66:69]
	v_mfma_f32_16x16x32_bf16 v[66:69], v[168:171], v[222:225], v[66:69]
	v_mfma_f32_16x16x32_bf16 v[70:73], v[156:159], v[222:225], v[70:73]
	v_mfma_f32_16x16x32_bf16 v[70:73], v[164:167], v[226:229], v[70:73]
	v_mfma_f32_16x16x32_bf16 v[86:89], v[164:167], v[218:221], v[86:89]
	v_mfma_f32_16x16x32_bf16 v[86:89], v[156:159], v[214:217], v[86:89]
	v_mfma_f32_16x16x32_bf16 v[102:105], v[156:159], v[184:187], v[102:105]
	v_mfma_f32_16x16x32_bf16 v[102:105], v[164:167], v[210:213], v[102:105]
	v_mfma_f32_16x16x32_bf16 v[118:121], v[164:167], v[180:183], v[118:121]
	s_barrier
	v_mfma_f32_16x16x32_bf16 v[118:121], v[156:159], v[176:179], v[118:121]
	s_setprio 0
	s_add_i32 s12, s56, s59
	ds_read_b128 v[176:179], v162 offset:16384
	ds_read_b128 v[180:183], v162 offset:17408
	ds_read_b128 v[184:187], v162 offset:18432
	ds_read_b128 v[210:213], v162 offset:19456
	ds_read_b128 v[214:217], v162 offset:20480
	ds_read_b128 v[218:221], v162 offset:21504
	ds_read_b128 v[222:225], v162 offset:22528
	ds_read_b128 v[226:229], v162 offset:23552
	s_mov_b32 m0, s12
	s_nop 0
	global_load_lds_dwordx4 v190, s[54:55]
	s_add_i32 m0, s12, 0x2000
	s_add_u32 s12, s54, 0x40000
	s_addc_u32 s13, s55, 0
	s_add_i32 s56, s75, s59
	global_load_lds_dwordx4 v150, s[54:55]
	s_mov_b32 m0, s56
	s_nop 0
	global_load_lds_dwordx4 v190, s[12:13]
	s_add_i32 m0, s56, 0x2000
	s_nop 0
	global_load_lds_dwordx4 v150, s[12:13]
	s_mov_b32 m0, s53
	s_nop 0
	global_load_lds_dwordx4 v146, s[62:63]
	s_mov_b32 m0, s60
	s_nop 0
	global_load_lds_dwordx4 v148, s[62:63]
	s_waitcnt vmcnt(8)
	s_waitcnt lgkmcnt(0)
	s_barrier
	s_setprio 1
	s_waitcnt lgkmcnt(0)
	v_mfma_f32_16x16x32_bf16 v[62:65], v[130:133], v[176:179], v[62:65]
	v_mfma_f32_16x16x32_bf16 v[62:65], v[134:137], v[180:183], v[62:65]
	v_mfma_f32_16x16x32_bf16 v[50:53], v[134:137], v[210:213], v[50:53]
	v_mfma_f32_16x16x32_bf16 v[50:53], v[130:133], v[184:187], v[50:53]
	v_mfma_f32_16x16x32_bf16 v[34:37], v[130:133], v[214:217], v[34:37]
	v_mfma_f32_16x16x32_bf16 v[34:37], v[134:137], v[218:221], v[34:37]
	v_mfma_f32_16x16x32_bf16 v[18:21], v[134:137], v[226:229], v[18:21]
	v_mfma_f32_16x16x32_bf16 v[18:21], v[130:133], v[222:225], v[18:21]
	v_mfma_f32_16x16x32_bf16 v[10:13], v[138:141], v[222:225], v[10:13]
	v_mfma_f32_16x16x32_bf16 v[10:13], v[142:145], v[226:229], v[10:13]
	v_mfma_f32_16x16x32_bf16 v[26:29], v[142:145], v[218:221], v[26:29]
	v_mfma_f32_16x16x32_bf16 v[26:29], v[138:141], v[214:217], v[26:29]
	v_mfma_f32_16x16x32_bf16 v[42:45], v[138:141], v[184:187], v[42:45]
	v_mfma_f32_16x16x32_bf16 v[42:45], v[142:145], v[210:213], v[42:45]
	v_mfma_f32_16x16x32_bf16 v[58:61], v[142:145], v[180:183], v[58:61]
	v_mfma_f32_16x16x32_bf16 v[58:61], v[138:141], v[176:179], v[58:61]
	v_mfma_f32_16x16x32_bf16 v[46:49], v[168:171], v[176:179], v[46:49]
	v_mfma_f32_16x16x32_bf16 v[46:49], v[172:175], v[180:183], v[46:49]
	v_mfma_f32_16x16x32_bf16 v[30:33], v[172:175], v[210:213], v[30:33]
	v_mfma_f32_16x16x32_bf16 v[30:33], v[168:171], v[184:187], v[30:33]
	v_mfma_f32_16x16x32_bf16 v[14:17], v[168:171], v[214:217], v[14:17]
	v_mfma_f32_16x16x32_bf16 v[14:17], v[172:175], v[218:221], v[14:17]
	v_mfma_f32_16x16x32_bf16 v[2:5], v[172:175], v[226:229], v[2:5]
	v_mfma_f32_16x16x32_bf16 v[2:5], v[168:171], v[222:225], v[2:5]
	v_mfma_f32_16x16x32_bf16 v[6:9], v[156:159], v[222:225], v[6:9]
	v_mfma_f32_16x16x32_bf16 v[6:9], v[164:167], v[226:229], v[6:9]
	v_mfma_f32_16x16x32_bf16 v[22:25], v[164:167], v[218:221], v[22:25]
	v_mfma_f32_16x16x32_bf16 v[22:25], v[156:159], v[214:217], v[22:25]
	v_mfma_f32_16x16x32_bf16 v[38:41], v[156:159], v[184:187], v[38:41]
	v_mfma_f32_16x16x32_bf16 v[38:41], v[164:167], v[210:213], v[38:41]
	v_mfma_f32_16x16x32_bf16 v[54:57], v[164:167], v[180:183], v[54:57]
	s_barrier
	v_mfma_f32_16x16x32_bf16 v[54:57], v[156:159], v[176:179], v[54:57]
	s_setprio 0
	s_add_i32 s56, 0, 0x18000
	s_add_i32 s75, 0, 0x1c000
	s_add_u32 s12, s62, 0x40000
	s_addc_u32 s13, s63, 0
	v_add_u32_e32 v142, s56, v160
	v_add_u32_e32 v163, s75, v160
	ds_read_b128 v[130:133], v142
	ds_read_b128 v[134:137], v142 offset:1024
	ds_read_b128 v[138:141], v142 offset:2048
	ds_read_b128 v[142:145], v142 offset:3072
	ds_read_b128 v[156:159], v163
	ds_read_b128 v[164:167], v163 offset:1024
	ds_read_b128 v[168:171], v163 offset:2048
	ds_read_b128 v[172:175], v163 offset:3072
	ds_read_b128 v[176:179], v162 offset:32768
	ds_read_b128 v[180:183], v162 offset:33792
	ds_read_b128 v[184:187], v162 offset:34816
	ds_read_b128 v[210:213], v162 offset:35840
	ds_read_b128 v[214:217], v162 offset:36864
	ds_read_b128 v[218:221], v162 offset:37888
	ds_read_b128 v[222:225], v162 offset:38912
	ds_read_b128 v[226:229], v162 offset:39936
	s_mov_b32 m0, s64
	s_nop 0
	global_load_lds_dwordx4 v146, s[12:13]
	s_mov_b32 m0, s65
	s_nop 0
	global_load_lds_dwordx4 v148, s[12:13]
	s_waitcnt vmcnt(8)
	s_waitcnt lgkmcnt(0)
	s_barrier
	s_setprio 1
	s_waitcnt lgkmcnt(0)
	v_mfma_f32_16x16x32_bf16 v[126:129], v[130:133], v[176:179], v[126:129]
	v_mfma_f32_16x16x32_bf16 v[126:129], v[134:137], v[180:183], v[126:129]
	v_mfma_f32_16x16x32_bf16 v[114:117], v[134:137], v[210:213], v[114:117]
	v_mfma_f32_16x16x32_bf16 v[114:117], v[130:133], v[184:187], v[114:117]
	v_mfma_f32_16x16x32_bf16 v[98:101], v[130:133], v[214:217], v[98:101]
	v_mfma_f32_16x16x32_bf16 v[98:101], v[134:137], v[218:221], v[98:101]
	v_mfma_f32_16x16x32_bf16 v[82:85], v[134:137], v[226:229], v[82:85]
	v_mfma_f32_16x16x32_bf16 v[82:85], v[130:133], v[222:225], v[82:85]
	v_mfma_f32_16x16x32_bf16 v[74:77], v[138:141], v[222:225], v[74:77]
	v_mfma_f32_16x16x32_bf16 v[74:77], v[142:145], v[226:229], v[74:77]
	v_mfma_f32_16x16x32_bf16 v[90:93], v[142:145], v[218:221], v[90:93]
	v_mfma_f32_16x16x32_bf16 v[90:93], v[138:141], v[214:217], v[90:93]
	v_mfma_f32_16x16x32_bf16 v[106:109], v[138:141], v[184:187], v[106:109]
	v_mfma_f32_16x16x32_bf16 v[106:109], v[142:145], v[210:213], v[106:109]
	v_mfma_f32_16x16x32_bf16 v[122:125], v[142:145], v[180:183], v[122:125]
	v_mfma_f32_16x16x32_bf16 v[122:125], v[138:141], v[176:179], v[122:125]
	v_mfma_f32_16x16x32_bf16 v[110:113], v[168:171], v[176:179], v[110:113]
	v_mfma_f32_16x16x32_bf16 v[110:113], v[172:175], v[180:183], v[110:113]
	v_mfma_f32_16x16x32_bf16 v[94:97], v[172:175], v[210:213], v[94:97]
	v_mfma_f32_16x16x32_bf16 v[94:97], v[168:171], v[184:187], v[94:97]
	v_mfma_f32_16x16x32_bf16 v[78:81], v[168:171], v[214:217], v[78:81]
	v_mfma_f32_16x16x32_bf16 v[78:81], v[172:175], v[218:221], v[78:81]
	v_mfma_f32_16x16x32_bf16 v[66:69], v[172:175], v[226:229], v[66:69]
	v_mfma_f32_16x16x32_bf16 v[66:69], v[168:171], v[222:225], v[66:69]
	v_mfma_f32_16x16x32_bf16 v[70:73], v[156:159], v[222:225], v[70:73]
	v_mfma_f32_16x16x32_bf16 v[70:73], v[164:167], v[226:229], v[70:73]
	v_mfma_f32_16x16x32_bf16 v[86:89], v[164:167], v[218:221], v[86:89]
	v_mfma_f32_16x16x32_bf16 v[86:89], v[156:159], v[214:217], v[86:89]
	v_mfma_f32_16x16x32_bf16 v[102:105], v[156:159], v[184:187], v[102:105]
	v_mfma_f32_16x16x32_bf16 v[102:105], v[164:167], v[210:213], v[102:105]
	v_mfma_f32_16x16x32_bf16 v[118:121], v[164:167], v[180:183], v[118:121]
	s_barrier
	v_mfma_f32_16x16x32_bf16 v[118:121], v[156:159], v[176:179], v[118:121]
	s_setprio 0
	s_add_i32 s12, s56, s59
	ds_read_b128 v[176:179], v162 offset:49152
	ds_read_b128 v[180:183], v162 offset:50176
	ds_read_b128 v[184:187], v162 offset:51200
	ds_read_b128 v[210:213], v162 offset:52224
	ds_read_b128 v[214:217], v162 offset:53248
	ds_read_b128 v[218:221], v162 offset:54272
	ds_read_b128 v[222:225], v162 offset:55296
	ds_read_b128 v[226:229], v162 offset:56320
	s_mov_b32 m0, s12
	s_nop 0
	global_load_lds_dwordx4 v231, s[54:55]
	s_add_i32 m0, s12, 0x2000
	s_add_u32 s12, s54, 0x40080
	s_addc_u32 s13, s55, 0
	global_load_lds_dwordx4 v230, s[54:55]
	s_add_i32 s54, s75, s59
	s_mov_b32 m0, s54
	s_nop 0
	global_load_lds_dwordx4 v190, s[12:13]
	s_add_i32 m0, s54, 0x2000
	s_nop 0
	global_load_lds_dwordx4 v150, s[12:13]
	s_mov_b32 m0, s66
	s_nop 0
	global_load_lds_dwordx4 v188, s[62:63]
	s_mov_b32 m0, s68
	s_nop 0
	global_load_lds_dwordx4 v189, s[62:63]
	s_waitcnt vmcnt(8)
	s_waitcnt lgkmcnt(0)
	s_barrier
	s_setprio 1
	s_waitcnt lgkmcnt(0)
	v_mfma_f32_16x16x32_bf16 v[62:65], v[130:133], v[176:179], v[62:65]
	v_mfma_f32_16x16x32_bf16 v[62:65], v[134:137], v[180:183], v[62:65]
	v_mfma_f32_16x16x32_bf16 v[50:53], v[134:137], v[210:213], v[50:53]
	v_mfma_f32_16x16x32_bf16 v[50:53], v[130:133], v[184:187], v[50:53]
	v_mfma_f32_16x16x32_bf16 v[34:37], v[130:133], v[214:217], v[34:37]
	v_mfma_f32_16x16x32_bf16 v[34:37], v[134:137], v[218:221], v[34:37]
	v_mfma_f32_16x16x32_bf16 v[18:21], v[134:137], v[226:229], v[18:21]
	v_mfma_f32_16x16x32_bf16 v[18:21], v[130:133], v[222:225], v[18:21]
	v_mfma_f32_16x16x32_bf16 v[10:13], v[138:141], v[222:225], v[10:13]
	v_mfma_f32_16x16x32_bf16 v[10:13], v[142:145], v[226:229], v[10:13]
	v_mfma_f32_16x16x32_bf16 v[26:29], v[142:145], v[218:221], v[26:29]
	v_mfma_f32_16x16x32_bf16 v[26:29], v[138:141], v[214:217], v[26:29]
	v_mfma_f32_16x16x32_bf16 v[42:45], v[138:141], v[184:187], v[42:45]
	v_mfma_f32_16x16x32_bf16 v[42:45], v[142:145], v[210:213], v[42:45]
	v_mfma_f32_16x16x32_bf16 v[58:61], v[142:145], v[180:183], v[58:61]
	v_mfma_f32_16x16x32_bf16 v[58:61], v[138:141], v[176:179], v[58:61]
	v_mfma_f32_16x16x32_bf16 v[46:49], v[168:171], v[176:179], v[46:49]
	v_mfma_f32_16x16x32_bf16 v[46:49], v[172:175], v[180:183], v[46:49]
	v_mfma_f32_16x16x32_bf16 v[30:33], v[172:175], v[210:213], v[30:33]
	v_mfma_f32_16x16x32_bf16 v[30:33], v[168:171], v[184:187], v[30:33]
	v_mfma_f32_16x16x32_bf16 v[14:17], v[168:171], v[214:217], v[14:17]
	v_mfma_f32_16x16x32_bf16 v[14:17], v[172:175], v[218:221], v[14:17]
	v_mfma_f32_16x16x32_bf16 v[2:5], v[172:175], v[226:229], v[2:5]
	v_mfma_f32_16x16x32_bf16 v[2:5], v[168:171], v[222:225], v[2:5]
	v_mfma_f32_16x16x32_bf16 v[6:9], v[156:159], v[222:225], v[6:9]
	v_mfma_f32_16x16x32_bf16 v[6:9], v[164:167], v[226:229], v[6:9]
	v_mfma_f32_16x16x32_bf16 v[22:25], v[164:167], v[218:221], v[22:25]
	v_mfma_f32_16x16x32_bf16 v[22:25], v[156:159], v[214:217], v[22:25]
	v_mfma_f32_16x16x32_bf16 v[38:41], v[156:159], v[184:187], v[38:41]
	v_mfma_f32_16x16x32_bf16 v[38:41], v[164:167], v[210:213], v[38:41]
	v_mfma_f32_16x16x32_bf16 v[54:57], v[164:167], v[180:183], v[54:57]
	s_barrier
	v_mfma_f32_16x16x32_bf16 v[54:57], v[156:159], v[176:179], v[54:57]
	s_setprio 0
	s_add_i32 s74, s74, 2
	s_add_u32 s40, s40, 0x100
	s_addc_u32 s41, s41, 0
	s_add_u32 s73, s73, 0x100
	s_addc_u32 s61, s61, 0
	s_cmp_gt_u32 s74, 13
	s_cbranch_scc0 .LBB0_692
	s_and_b64 vcc, exec, s[30:31]
	s_cbranch_vccz .LBB0_695
	s_barrier

.LBB0_777:
	s_add_u32 s12, s50, 0xfff00080
	s_addc_u32 s13, s51, -1
	s_add_i32 s56, 0, 0x10000
	s_cmp_eq_u32 s72, 60
	s_cselect_b32 s55, s43, s13
	s_cselect_b32 s54, s49, s12
	s_cselect_b32 s53, s41, s61
	s_cselect_b32 s52, s70, s71
	s_add_i32 s73, 0, 0x14000
	v_add_u32_e32 v142, s56, v193
	v_add_u32_e32 v158, s73, v193
	ds_read_b128 v[130:133], v142
	ds_read_b128 v[134:137], v142 offset:1024
	ds_read_b128 v[138:141], v142 offset:2048
	ds_read_b128 v[142:145], v142 offset:3072
	ds_read_b128 v[146:149], v158
	ds_read_b128 v[150:153], v158 offset:1024
	ds_read_b128 v[154:157], v158 offset:2048
	ds_read_b128 v[158:161], v158 offset:3072
	ds_read_b128 v[162:165], v197
	ds_read_b128 v[166:169], v197 offset:1024
	ds_read_b128 v[170:173], v197 offset:2048
	ds_read_b128 v[174:177], v197 offset:3072
	ds_read_b128 v[178:181], v197 offset:4096
	ds_read_b128 v[182:185], v197 offset:5120
	ds_read_b128 v[186:189], v197 offset:6144
	ds_read_b128 v[220:223], v197 offset:7168
	s_add_i32 m0, s33, 0xc000
	s_nop 0
	global_load_lds_dwordx4 v216, s[50:51]
	s_add_i32 m0, s33, 0xe000
	s_nop 0
	global_load_lds_dwordx4 v218, s[50:51]
	s_waitcnt vmcnt(8)
	s_waitcnt lgkmcnt(0)
	s_barrier
	s_setprio 1
	s_waitcnt lgkmcnt(0)
	v_mfma_f32_16x16x32_bf16 v[126:129], v[130:133], v[162:165], v[126:129]
	v_mfma_f32_16x16x32_bf16 v[126:129], v[134:137], v[166:169], v[126:129]
	v_mfma_f32_16x16x32_bf16 v[110:113], v[134:137], v[174:177], v[110:113]
	v_mfma_f32_16x16x32_bf16 v[110:113], v[130:133], v[170:173], v[110:113]
	v_mfma_f32_16x16x32_bf16 v[98:101], v[130:133], v[178:181], v[98:101]
	v_mfma_f32_16x16x32_bf16 v[98:101], v[134:137], v[182:185], v[98:101]
	v_mfma_f32_16x16x32_bf16 v[82:85], v[134:137], v[220:223], v[82:85]
	v_mfma_f32_16x16x32_bf16 v[82:85], v[130:133], v[186:189], v[82:85]
	v_mfma_f32_16x16x32_bf16 v[74:77], v[138:141], v[186:189], v[74:77]
	v_mfma_f32_16x16x32_bf16 v[74:77], v[142:145], v[220:223], v[74:77]
	v_mfma_f32_16x16x32_bf16 v[90:93], v[142:145], v[182:185], v[90:93]
	v_mfma_f32_16x16x32_bf16 v[90:93], v[138:141], v[178:181], v[90:93]
	v_mfma_f32_16x16x32_bf16 v[106:109], v[138:141], v[170:173], v[106:109]
	v_mfma_f32_16x16x32_bf16 v[106:109], v[142:145], v[174:177], v[106:109]
	v_mfma_f32_16x16x32_bf16 v[122:125], v[142:145], v[166:169], v[122:125]
	v_mfma_f32_16x16x32_bf16 v[122:125], v[138:141], v[162:165], v[122:125]
	v_mfma_f32_16x16x32_bf16 v[114:117], v[154:157], v[162:165], v[114:117]
	v_mfma_f32_16x16x32_bf16 v[114:117], v[158:161], v[166:169], v[114:117]
	v_mfma_f32_16x16x32_bf16 v[94:97], v[158:161], v[174:177], v[94:97]
	v_mfma_f32_16x16x32_bf16 v[94:97], v[154:157], v[170:173], v[94:97]
	v_mfma_f32_16x16x32_bf16 v[78:81], v[154:157], v[178:181], v[78:81]
	v_mfma_f32_16x16x32_bf16 v[78:81], v[158:161], v[182:185], v[78:81]
	v_mfma_f32_16x16x32_bf16 v[66:69], v[158:161], v[220:223], v[66:69]
	v_mfma_f32_16x16x32_bf16 v[66:69], v[154:157], v[186:189], v[66:69]
	v_mfma_f32_16x16x32_bf16 v[70:73], v[146:149], v[186:189], v[70:73]
	v_mfma_f32_16x16x32_bf16 v[70:73], v[150:153], v[220:223], v[70:73]
	v_mfma_f32_16x16x32_bf16 v[86:89], v[150:153], v[182:185], v[86:89]
	v_mfma_f32_16x16x32_bf16 v[86:89], v[146:149], v[178:181], v[86:89]
	v_mfma_f32_16x16x32_bf16 v[102:105], v[146:149], v[170:173], v[102:105]
	v_mfma_f32_16x16x32_bf16 v[102:105], v[150:153], v[174:177], v[102:105]
	v_mfma_f32_16x16x32_bf16 v[118:121], v[150:153], v[166:169], v[118:121]
	s_barrier
	v_mfma_f32_16x16x32_bf16 v[118:121], v[146:149], v[162:165], v[118:121]
	s_setprio 0
	s_add_i32 s12, s56, s29
	ds_read_b128 v[162:165], v197 offset:16384
	ds_read_b128 v[166:169], v197 offset:17408
	ds_read_b128 v[170:173], v197 offset:18432
	ds_read_b128 v[174:177], v197 offset:19456
	ds_read_b128 v[178:181], v197 offset:20480
	ds_read_b128 v[182:185], v197 offset:21504
	ds_read_b128 v[186:189], v197 offset:22528
	ds_read_b128 v[220:223], v197 offset:23552
	s_mov_b32 m0, s12
	s_nop 0
	global_load_lds_dwordx4 v190, s[52:53]
	s_add_i32 m0, s12, 0x2000
	s_add_u32 s12, s52, 0x100000
	s_addc_u32 s13, s53, 0
	s_add_i32 s56, s73, s29
	global_load_lds_dwordx4 v214, s[52:53]
	s_mov_b32 m0, s56
	s_nop 0
	global_load_lds_dwordx4 v190, s[12:13]
	s_add_i32 m0, s56, 0x2000
	s_nop 0
	global_load_lds_dwordx4 v214, s[12:13]
	s_mov_b32 m0, s33
	s_nop 0
	global_load_lds_dwordx4 v210, s[54:55]
	s_mov_b32 m0, s62
	s_nop 0
	global_load_lds_dwordx4 v212, s[54:55]
	s_waitcnt vmcnt(8)
	s_waitcnt lgkmcnt(0)
	s_barrier
	s_setprio 1
	s_waitcnt lgkmcnt(0)
	v_mfma_f32_16x16x32_bf16 v[62:65], v[130:133], v[162:165], v[62:65]
	v_mfma_f32_16x16x32_bf16 v[62:65], v[134:137], v[166:169], v[62:65]
	v_mfma_f32_16x16x32_bf16 v[50:53], v[134:137], v[174:177], v[50:53]
	v_mfma_f32_16x16x32_bf16 v[50:53], v[130:133], v[170:173], v[50:53]
	v_mfma_f32_16x16x32_bf16 v[34:37], v[130:133], v[178:181], v[34:37]
	v_mfma_f32_16x16x32_bf16 v[34:37], v[134:137], v[182:185], v[34:37]
	v_mfma_f32_16x16x32_bf16 v[18:21], v[134:137], v[220:223], v[18:21]
	v_mfma_f32_16x16x32_bf16 v[18:21], v[130:133], v[186:189], v[18:21]
	v_mfma_f32_16x16x32_bf16 v[10:13], v[138:141], v[186:189], v[10:13]
	v_mfma_f32_16x16x32_bf16 v[10:13], v[142:145], v[220:223], v[10:13]
	v_mfma_f32_16x16x32_bf16 v[26:29], v[142:145], v[182:185], v[26:29]
	v_mfma_f32_16x16x32_bf16 v[26:29], v[138:141], v[178:181], v[26:29]
	v_mfma_f32_16x16x32_bf16 v[42:45], v[138:141], v[170:173], v[42:45]
	v_mfma_f32_16x16x32_bf16 v[42:45], v[142:145], v[174:177], v[42:45]
	v_mfma_f32_16x16x32_bf16 v[58:61], v[142:145], v[166:169], v[58:61]
	v_mfma_f32_16x16x32_bf16 v[58:61], v[138:141], v[162:165], v[58:61]
	v_mfma_f32_16x16x32_bf16 v[46:49], v[154:157], v[162:165], v[46:49]
	v_mfma_f32_16x16x32_bf16 v[46:49], v[158:161], v[166:169], v[46:49]
	v_mfma_f32_16x16x32_bf16 v[30:33], v[158:161], v[174:177], v[30:33]
	v_mfma_f32_16x16x32_bf16 v[30:33], v[154:157], v[170:173], v[30:33]
	v_mfma_f32_16x16x32_bf16 v[14:17], v[154:157], v[178:181], v[14:17]
	v_mfma_f32_16x16x32_bf16 v[14:17], v[158:161], v[182:185], v[14:17]
	v_mfma_f32_16x16x32_bf16 v[2:5], v[158:161], v[220:223], v[2:5]
	v_mfma_f32_16x16x32_bf16 v[2:5], v[154:157], v[186:189], v[2:5]
	v_mfma_f32_16x16x32_bf16 v[6:9], v[146:149], v[186:189], v[6:9]
	v_mfma_f32_16x16x32_bf16 v[6:9], v[150:153], v[220:223], v[6:9]
	v_mfma_f32_16x16x32_bf16 v[22:25], v[150:153], v[182:185], v[22:25]
	v_mfma_f32_16x16x32_bf16 v[22:25], v[146:149], v[178:181], v[22:25]
	v_mfma_f32_16x16x32_bf16 v[38:41], v[146:149], v[170:173], v[38:41]
	v_mfma_f32_16x16x32_bf16 v[38:41], v[150:153], v[174:177], v[38:41]
	v_mfma_f32_16x16x32_bf16 v[54:57], v[150:153], v[166:169], v[54:57]
	s_barrier
	v_mfma_f32_16x16x32_bf16 v[54:57], v[146:149], v[162:165], v[54:57]
	s_setprio 0
	s_add_i32 s56, 0, 0x18000
	s_add_i32 s73, 0, 0x1c000
	s_add_u32 s12, s54, 0x100000
	s_addc_u32 s13, s55, 0
	v_add_u32_e32 v142, s56, v193
	v_add_u32_e32 v158, s73, v193
	ds_read_b128 v[130:133], v142
	ds_read_b128 v[134:137], v142 offset:1024
	ds_read_b128 v[138:141], v142 offset:2048
	ds_read_b128 v[142:145], v142 offset:3072
	ds_read_b128 v[146:149], v158
	ds_read_b128 v[150:153], v158 offset:1024
	ds_read_b128 v[154:157], v158 offset:2048
	ds_read_b128 v[158:161], v158 offset:3072
	ds_read_b128 v[162:165], v197 offset:32768
	ds_read_b128 v[166:169], v197 offset:33792
	ds_read_b128 v[170:173], v197 offset:34816
	ds_read_b128 v[174:177], v197 offset:35840
	ds_read_b128 v[178:181], v197 offset:36864
	ds_read_b128 v[182:185], v197 offset:37888
	ds_read_b128 v[186:189], v197 offset:38912
	ds_read_b128 v[220:223], v197 offset:39936
	s_mov_b32 m0, s63
	s_nop 0
	global_load_lds_dwordx4 v210, s[12:13]
	s_mov_b32 m0, s64
	s_nop 0
	global_load_lds_dwordx4 v212, s[12:13]
	s_waitcnt vmcnt(8)
	s_waitcnt lgkmcnt(0)
	s_barrier
	s_setprio 1
	s_waitcnt lgkmcnt(0)
	v_mfma_f32_16x16x32_bf16 v[126:129], v[130:133], v[162:165], v[126:129]
	v_mfma_f32_16x16x32_bf16 v[126:129], v[134:137], v[166:169], v[126:129]
	v_mfma_f32_16x16x32_bf16 v[110:113], v[134:137], v[174:177], v[110:113]
	v_mfma_f32_16x16x32_bf16 v[110:113], v[130:133], v[170:173], v[110:113]
	v_mfma_f32_16x16x32_bf16 v[98:101], v[130:133], v[178:181], v[98:101]
	v_mfma_f32_16x16x32_bf16 v[98:101], v[134:137], v[182:185], v[98:101]
	v_mfma_f32_16x16x32_bf16 v[82:85], v[134:137], v[220:223], v[82:85]
	v_mfma_f32_16x16x32_bf16 v[82:85], v[130:133], v[186:189], v[82:85]
	v_mfma_f32_16x16x32_bf16 v[74:77], v[138:141], v[186:189], v[74:77]
	v_mfma_f32_16x16x32_bf16 v[74:77], v[142:145], v[220:223], v[74:77]
	v_mfma_f32_16x16x32_bf16 v[90:93], v[142:145], v[182:185], v[90:93]
	v_mfma_f32_16x16x32_bf16 v[90:93], v[138:141], v[178:181], v[90:93]
	v_mfma_f32_16x16x32_bf16 v[106:109], v[138:141], v[170:173], v[106:109]
	v_mfma_f32_16x16x32_bf16 v[106:109], v[142:145], v[174:177], v[106:109]
	v_mfma_f32_16x16x32_bf16 v[122:125], v[142:145], v[166:169], v[122:125]
	v_mfma_f32_16x16x32_bf16 v[122:125], v[138:141], v[162:165], v[122:125]
	v_mfma_f32_16x16x32_bf16 v[114:117], v[154:157], v[162:165], v[114:117]
	v_mfma_f32_16x16x32_bf16 v[114:117], v[158:161], v[166:169], v[114:117]
	v_mfma_f32_16x16x32_bf16 v[94:97], v[158:161], v[174:177], v[94:97]
	v_mfma_f32_16x16x32_bf16 v[94:97], v[154:157], v[170:173], v[94:97]
	v_mfma_f32_16x16x32_bf16 v[78:81], v[154:157], v[178:181], v[78:81]
	v_mfma_f32_16x16x32_bf16 v[78:81], v[158:161], v[182:185], v[78:81]
	v_mfma_f32_16x16x32_bf16 v[66:69], v[158:161], v[220:223], v[66:69]
	v_mfma_f32_16x16x32_bf16 v[66:69], v[154:157], v[186:189], v[66:69]
	v_mfma_f32_16x16x32_bf16 v[70:73], v[146:149], v[186:189], v[70:73]
	v_mfma_f32_16x16x32_bf16 v[70:73], v[150:153], v[220:223], v[70:73]
	v_mfma_f32_16x16x32_bf16 v[86:89], v[150:153], v[182:185], v[86:89]
	v_mfma_f32_16x16x32_bf16 v[86:89], v[146:149], v[178:181], v[86:89]
	v_mfma_f32_16x16x32_bf16 v[102:105], v[146:149], v[170:173], v[102:105]
	v_mfma_f32_16x16x32_bf16 v[102:105], v[150:153], v[174:177], v[102:105]
	v_mfma_f32_16x16x32_bf16 v[118:121], v[150:153], v[166:169], v[118:121]
	s_barrier
	v_mfma_f32_16x16x32_bf16 v[118:121], v[146:149], v[162:165], v[118:121]
	s_setprio 0
	s_add_i32 s12, s56, s29
	ds_read_b128 v[162:165], v197 offset:49152
	ds_read_b128 v[166:169], v197 offset:50176
	ds_read_b128 v[170:173], v197 offset:51200
	ds_read_b128 v[174:177], v197 offset:52224
	ds_read_b128 v[178:181], v197 offset:53248
	ds_read_b128 v[182:185], v197 offset:54272
	ds_read_b128 v[186:189], v197 offset:55296
	ds_read_b128 v[220:223], v197 offset:56320
	s_mov_b32 m0, s12
	s_nop 0
	global_load_lds_dwordx4 v224, s[52:53]
	s_add_i32 m0, s12, 0x2000
	s_add_u32 s12, s52, 0x100080
	s_addc_u32 s13, s53, 0
	global_load_lds_dwordx4 v227, s[52:53]
	s_add_i32 s52, s73, s29
	s_mov_b32 m0, s52
	s_nop 0
	global_load_lds_dwordx4 v190, s[12:13]
	s_add_i32 m0, s52, 0x2000
	s_nop 0
	global_load_lds_dwordx4 v214, s[12:13]
	s_mov_b32 m0, s65
	s_nop 0
	global_load_lds_dwordx4 v225, s[54:55]
	s_mov_b32 m0, s66
	s_nop 0
	global_load_lds_dwordx4 v226, s[54:55]
	s_waitcnt vmcnt(8)
	s_waitcnt lgkmcnt(0)
	s_barrier
	s_setprio 1
	s_waitcnt lgkmcnt(0)
	v_mfma_f32_16x16x32_bf16 v[62:65], v[130:133], v[162:165], v[62:65]
	v_mfma_f32_16x16x32_bf16 v[62:65], v[134:137], v[166:169], v[62:65]
	v_mfma_f32_16x16x32_bf16 v[50:53], v[134:137], v[174:177], v[50:53]
	v_mfma_f32_16x16x32_bf16 v[50:53], v[130:133], v[170:173], v[50:53]
	v_mfma_f32_16x16x32_bf16 v[34:37], v[130:133], v[178:181], v[34:37]
	v_mfma_f32_16x16x32_bf16 v[34:37], v[134:137], v[182:185], v[34:37]
	v_mfma_f32_16x16x32_bf16 v[18:21], v[134:137], v[220:223], v[18:21]
	v_mfma_f32_16x16x32_bf16 v[18:21], v[130:133], v[186:189], v[18:21]
	v_mfma_f32_16x16x32_bf16 v[10:13], v[138:141], v[186:189], v[10:13]
	v_mfma_f32_16x16x32_bf16 v[10:13], v[142:145], v[220:223], v[10:13]
	v_mfma_f32_16x16x32_bf16 v[26:29], v[142:145], v[182:185], v[26:29]
	v_mfma_f32_16x16x32_bf16 v[26:29], v[138:141], v[178:181], v[26:29]
	v_mfma_f32_16x16x32_bf16 v[42:45], v[138:141], v[170:173], v[42:45]
	v_mfma_f32_16x16x32_bf16 v[42:45], v[142:145], v[174:177], v[42:45]
	v_mfma_f32_16x16x32_bf16 v[58:61], v[142:145], v[166:169], v[58:61]
	v_mfma_f32_16x16x32_bf16 v[58:61], v[138:141], v[162:165], v[58:61]
	v_mfma_f32_16x16x32_bf16 v[46:49], v[154:157], v[162:165], v[46:49]
	v_mfma_f32_16x16x32_bf16 v[46:49], v[158:161], v[166:169], v[46:49]
	v_mfma_f32_16x16x32_bf16 v[30:33], v[158:161], v[174:177], v[30:33]
	v_mfma_f32_16x16x32_bf16 v[30:33], v[154:157], v[170:173], v[30:33]
	v_mfma_f32_16x16x32_bf16 v[14:17], v[154:157], v[178:181], v[14:17]
	v_mfma_f32_16x16x32_bf16 v[14:17], v[158:161], v[182:185], v[14:17]
	v_mfma_f32_16x16x32_bf16 v[2:5], v[158:161], v[220:223], v[2:5]
	v_mfma_f32_16x16x32_bf16 v[2:5], v[154:157], v[186:189], v[2:5]
	v_mfma_f32_16x16x32_bf16 v[6:9], v[146:149], v[186:189], v[6:9]
	v_mfma_f32_16x16x32_bf16 v[6:9], v[150:153], v[220:223], v[6:9]
	v_mfma_f32_16x16x32_bf16 v[22:25], v[150:153], v[182:185], v[22:25]
	v_mfma_f32_16x16x32_bf16 v[22:25], v[146:149], v[178:181], v[22:25]
	v_mfma_f32_16x16x32_bf16 v[38:41], v[146:149], v[170:173], v[38:41]
	v_mfma_f32_16x16x32_bf16 v[38:41], v[150:153], v[174:177], v[38:41]
	v_mfma_f32_16x16x32_bf16 v[54:57], v[150:153], v[166:169], v[54:57]
	s_barrier
	v_mfma_f32_16x16x32_bf16 v[54:57], v[146:149], v[162:165], v[54:57]
	s_setprio 0
	s_add_i32 s72, s72, 2
	s_add_u32 s50, s50, 0x100
	s_addc_u32 s51, s51, 0
	s_add_u32 s71, s71, 0x100
	s_addc_u32 s61, s61, 0
	s_cmp_gt_u32 s72, 61
	s_cbranch_scc0 .LBB0_777
	s_and_b64 vcc, exec, s[30:31]
	s_cbranch_vccz .LBB0_780
	s_barrier

.LBB0_902:
	s_add_u32 s12, s22, 0xfff00080
	s_addc_u32 s13, s23, -1
	s_add_i32 s56, 0, 0x10000
	s_cmp_eq_u32 s47, 60
	s_cselect_b32 s53, s5, s13
	s_cselect_b32 s52, s10, s12
	s_cselect_b32 s31, s25, s45
	s_cselect_b32 s30, s29, s33
	s_add_i32 s61, 0, 0x14000
	v_add_u32_e32 v147, s56, v144
	ds_read_b128 v[140:143], v147
	ds_read_b128 v[148:151], v147 offset:1024
	ds_read_b128 v[152:155], v147 offset:2048
	ds_read_b128 v[156:159], v147 offset:3072
	v_add_u32_e32 v147, s61, v144
	ds_read_b128 v[160:163], v147
	ds_read_b128 v[164:167], v147 offset:1024
	ds_read_b128 v[168:171], v147 offset:2048
	ds_read_b128 v[172:175], v147 offset:3072
	ds_read_b128 v[176:179], v146
	ds_read_b128 v[180:183], v146 offset:1024
	ds_read_b128 v[184:187], v146 offset:2048
	ds_read_b128 v[210:213], v146 offset:3072
	ds_read_b128 v[214:217], v146 offset:4096
	ds_read_b128 v[218:221], v146 offset:5120
	ds_read_b128 v[222:225], v146 offset:6144
	ds_read_b128 v[226:229], v146 offset:7168
	s_add_i32 m0, s63, 0xc000
	s_nop 0
	global_load_lds_dwordx4 v136, s[22:23]
	s_add_i32 m0, s63, 0xe000
	s_nop 0
	global_load_lds_dwordx4 v138, s[22:23]
	s_waitcnt vmcnt(8)
	s_waitcnt lgkmcnt(0)
	s_barrier
	s_setprio 1
	s_waitcnt lgkmcnt(0)
	v_mfma_f32_16x16x32_bf16 v[126:129], v[140:143], v[176:179], v[126:129]
	v_mfma_f32_16x16x32_bf16 v[126:129], v[148:151], v[180:183], v[126:129]
	v_mfma_f32_16x16x32_bf16 v[110:113], v[148:151], v[210:213], v[110:113]
	v_mfma_f32_16x16x32_bf16 v[110:113], v[140:143], v[184:187], v[110:113]
	v_mfma_f32_16x16x32_bf16 v[94:97], v[140:143], v[214:217], v[94:97]
	v_mfma_f32_16x16x32_bf16 v[94:97], v[148:151], v[218:221], v[94:97]
	v_mfma_f32_16x16x32_bf16 v[78:81], v[148:151], v[226:229], v[78:81]
	v_mfma_f32_16x16x32_bf16 v[78:81], v[140:143], v[222:225], v[78:81]
	v_mfma_f32_16x16x32_bf16 v[70:73], v[152:155], v[222:225], v[70:73]
	v_mfma_f32_16x16x32_bf16 v[70:73], v[156:159], v[226:229], v[70:73]
	v_mfma_f32_16x16x32_bf16 v[86:89], v[156:159], v[218:221], v[86:89]
	v_mfma_f32_16x16x32_bf16 v[86:89], v[152:155], v[214:217], v[86:89]
	v_mfma_f32_16x16x32_bf16 v[102:105], v[152:155], v[184:187], v[102:105]
	v_mfma_f32_16x16x32_bf16 v[102:105], v[156:159], v[210:213], v[102:105]
	v_mfma_f32_16x16x32_bf16 v[118:121], v[156:159], v[180:183], v[118:121]
	v_mfma_f32_16x16x32_bf16 v[118:121], v[152:155], v[176:179], v[118:121]
	v_mfma_f32_16x16x32_bf16 v[114:117], v[168:171], v[176:179], v[114:117]
	v_mfma_f32_16x16x32_bf16 v[114:117], v[172:175], v[180:183], v[114:117]
	v_mfma_f32_16x16x32_bf16 v[98:101], v[172:175], v[210:213], v[98:101]
	v_mfma_f32_16x16x32_bf16 v[98:101], v[168:171], v[184:187], v[98:101]
	v_mfma_f32_16x16x32_bf16 v[82:85], v[168:171], v[214:217], v[82:85]
	v_mfma_f32_16x16x32_bf16 v[82:85], v[172:175], v[218:221], v[82:85]
	v_mfma_f32_16x16x32_bf16 v[66:69], v[172:175], v[226:229], v[66:69]
	v_mfma_f32_16x16x32_bf16 v[66:69], v[168:171], v[222:225], v[66:69]
	v_mfma_f32_16x16x32_bf16 v[74:77], v[160:163], v[222:225], v[74:77]
	v_mfma_f32_16x16x32_bf16 v[74:77], v[164:167], v[226:229], v[74:77]
	v_mfma_f32_16x16x32_bf16 v[90:93], v[164:167], v[218:221], v[90:93]
	v_mfma_f32_16x16x32_bf16 v[90:93], v[160:163], v[214:217], v[90:93]
	v_mfma_f32_16x16x32_bf16 v[106:109], v[160:163], v[184:187], v[106:109]
	v_mfma_f32_16x16x32_bf16 v[106:109], v[164:167], v[210:213], v[106:109]
	v_mfma_f32_16x16x32_bf16 v[122:125], v[164:167], v[180:183], v[122:125]
	s_barrier
	v_mfma_f32_16x16x32_bf16 v[122:125], v[160:163], v[176:179], v[122:125]
	s_setprio 0
	s_add_i32 s12, s56, s60
	ds_read_b128 v[176:179], v146 offset:16384
	ds_read_b128 v[180:183], v146 offset:17408
	ds_read_b128 v[184:187], v146 offset:18432
	ds_read_b128 v[210:213], v146 offset:19456
	ds_read_b128 v[214:217], v146 offset:20480
	ds_read_b128 v[218:221], v146 offset:21504
	ds_read_b128 v[222:225], v146 offset:22528
	ds_read_b128 v[226:229], v146 offset:23552
	s_mov_b32 m0, s12
	s_nop 0
	global_load_lds_dwordx4 v190, s[30:31]
	s_add_i32 m0, s12, 0x2000
	s_add_u32 s12, s30, 0x100000
	s_addc_u32 s13, s31, 0
	s_add_i32 s56, s61, s60
	global_load_lds_dwordx4 v130, s[30:31]
	s_mov_b32 m0, s56
	s_nop 0
	global_load_lds_dwordx4 v190, s[12:13]
	s_add_i32 m0, s56, 0x2000
	s_nop 0
	global_load_lds_dwordx4 v130, s[12:13]
	s_mov_b32 m0, s63
	s_nop 0
	global_load_lds_dwordx4 v134, s[52:53]
	s_mov_b32 m0, s64
	s_nop 0
	global_load_lds_dwordx4 v132, s[52:53]
	s_waitcnt vmcnt(8)
	s_waitcnt lgkmcnt(0)
	s_barrier
	s_setprio 1
	s_waitcnt lgkmcnt(0)
	v_mfma_f32_16x16x32_bf16 v[62:65], v[140:143], v[176:179], v[62:65]
	v_mfma_f32_16x16x32_bf16 v[62:65], v[148:151], v[180:183], v[62:65]
	v_mfma_f32_16x16x32_bf16 v[46:49], v[148:151], v[210:213], v[46:49]
	v_mfma_f32_16x16x32_bf16 v[46:49], v[140:143], v[184:187], v[46:49]
	v_mfma_f32_16x16x32_bf16 v[30:33], v[140:143], v[214:217], v[30:33]
	v_mfma_f32_16x16x32_bf16 v[30:33], v[148:151], v[218:221], v[30:33]
	v_mfma_f32_16x16x32_bf16 v[14:17], v[148:151], v[226:229], v[14:17]
	v_mfma_f32_16x16x32_bf16 v[14:17], v[140:143], v[222:225], v[14:17]
	v_mfma_f32_16x16x32_bf16 v[6:9], v[152:155], v[222:225], v[6:9]
	v_mfma_f32_16x16x32_bf16 v[6:9], v[156:159], v[226:229], v[6:9]
	v_mfma_f32_16x16x32_bf16 v[22:25], v[156:159], v[218:221], v[22:25]
	v_mfma_f32_16x16x32_bf16 v[22:25], v[152:155], v[214:217], v[22:25]
	v_mfma_f32_16x16x32_bf16 v[38:41], v[152:155], v[184:187], v[38:41]
	v_mfma_f32_16x16x32_bf16 v[38:41], v[156:159], v[210:213], v[38:41]
	v_mfma_f32_16x16x32_bf16 v[54:57], v[156:159], v[180:183], v[54:57]
	v_mfma_f32_16x16x32_bf16 v[54:57], v[152:155], v[176:179], v[54:57]
	v_mfma_f32_16x16x32_bf16 v[50:53], v[168:171], v[176:179], v[50:53]
	v_mfma_f32_16x16x32_bf16 v[50:53], v[172:175], v[180:183], v[50:53]
	v_mfma_f32_16x16x32_bf16 v[34:37], v[172:175], v[210:213], v[34:37]
	v_mfma_f32_16x16x32_bf16 v[34:37], v[168:171], v[184:187], v[34:37]
	v_mfma_f32_16x16x32_bf16 v[18:21], v[168:171], v[214:217], v[18:21]
	v_mfma_f32_16x16x32_bf16 v[18:21], v[172:175], v[218:221], v[18:21]
	v_mfma_f32_16x16x32_bf16 v[2:5], v[172:175], v[226:229], v[2:5]
	v_mfma_f32_16x16x32_bf16 v[2:5], v[168:171], v[222:225], v[2:5]
	v_mfma_f32_16x16x32_bf16 v[10:13], v[160:163], v[222:225], v[10:13]
	v_mfma_f32_16x16x32_bf16 v[10:13], v[164:167], v[226:229], v[10:13]
	v_mfma_f32_16x16x32_bf16 v[26:29], v[164:167], v[218:221], v[26:29]
	v_mfma_f32_16x16x32_bf16 v[26:29], v[160:163], v[214:217], v[26:29]
	v_mfma_f32_16x16x32_bf16 v[42:45], v[160:163], v[184:187], v[42:45]
	v_mfma_f32_16x16x32_bf16 v[42:45], v[164:167], v[210:213], v[42:45]
	v_mfma_f32_16x16x32_bf16 v[58:61], v[164:167], v[180:183], v[58:61]
	s_barrier
	v_mfma_f32_16x16x32_bf16 v[58:61], v[160:163], v[176:179], v[58:61]
	s_setprio 0
	s_add_i32 s56, 0, 0x18000
	s_add_i32 s61, 0, 0x1c000
	s_add_u32 s12, s52, 0x100000
	s_addc_u32 s13, s53, 0
	v_add_u32_e32 v147, s56, v144
	ds_read_b128 v[140:143], v147
	ds_read_b128 v[148:151], v147 offset:1024
	ds_read_b128 v[152:155], v147 offset:2048
	ds_read_b128 v[156:159], v147 offset:3072
	v_add_u32_e32 v147, s61, v144
	ds_read_b128 v[160:163], v147
	ds_read_b128 v[164:167], v147 offset:1024
	ds_read_b128 v[168:171], v147 offset:2048
	ds_read_b128 v[172:175], v147 offset:3072
	ds_read_b128 v[176:179], v146 offset:32768
	ds_read_b128 v[180:183], v146 offset:33792
	ds_read_b128 v[184:187], v146 offset:34816
	ds_read_b128 v[210:213], v146 offset:35840
	ds_read_b128 v[214:217], v146 offset:36864
	ds_read_b128 v[218:221], v146 offset:37888
	ds_read_b128 v[222:225], v146 offset:38912
	ds_read_b128 v[226:229], v146 offset:39936
	s_mov_b32 m0, s65
	s_nop 0
	global_load_lds_dwordx4 v134, s[12:13]
	s_mov_b32 m0, s66
	s_nop 0
	global_load_lds_dwordx4 v132, s[12:13]
	s_waitcnt vmcnt(8)
	s_waitcnt lgkmcnt(0)
	s_barrier
	s_setprio 1
	s_waitcnt lgkmcnt(0)
	v_mfma_f32_16x16x32_bf16 v[126:129], v[140:143], v[176:179], v[126:129]
	v_mfma_f32_16x16x32_bf16 v[126:129], v[148:151], v[180:183], v[126:129]
	v_mfma_f32_16x16x32_bf16 v[110:113], v[148:151], v[210:213], v[110:113]
	v_mfma_f32_16x16x32_bf16 v[110:113], v[140:143], v[184:187], v[110:113]
	v_mfma_f32_16x16x32_bf16 v[94:97], v[140:143], v[214:217], v[94:97]
	v_mfma_f32_16x16x32_bf16 v[94:97], v[148:151], v[218:221], v[94:97]
	v_mfma_f32_16x16x32_bf16 v[78:81], v[148:151], v[226:229], v[78:81]
	v_mfma_f32_16x16x32_bf16 v[78:81], v[140:143], v[222:225], v[78:81]
	v_mfma_f32_16x16x32_bf16 v[70:73], v[152:155], v[222:225], v[70:73]
	v_mfma_f32_16x16x32_bf16 v[70:73], v[156:159], v[226:229], v[70:73]
	v_mfma_f32_16x16x32_bf16 v[86:89], v[156:159], v[218:221], v[86:89]
	v_mfma_f32_16x16x32_bf16 v[86:89], v[152:155], v[214:217], v[86:89]
	v_mfma_f32_16x16x32_bf16 v[102:105], v[152:155], v[184:187], v[102:105]
	v_mfma_f32_16x16x32_bf16 v[102:105], v[156:159], v[210:213], v[102:105]
	v_mfma_f32_16x16x32_bf16 v[118:121], v[156:159], v[180:183], v[118:121]
	v_mfma_f32_16x16x32_bf16 v[118:121], v[152:155], v[176:179], v[118:121]
	v_mfma_f32_16x16x32_bf16 v[114:117], v[168:171], v[176:179], v[114:117]
	v_mfma_f32_16x16x32_bf16 v[114:117], v[172:175], v[180:183], v[114:117]
	v_mfma_f32_16x16x32_bf16 v[98:101], v[172:175], v[210:213], v[98:101]
	v_mfma_f32_16x16x32_bf16 v[98:101], v[168:171], v[184:187], v[98:101]
	v_mfma_f32_16x16x32_bf16 v[82:85], v[168:171], v[214:217], v[82:85]
	v_mfma_f32_16x16x32_bf16 v[82:85], v[172:175], v[218:221], v[82:85]
	v_mfma_f32_16x16x32_bf16 v[66:69], v[172:175], v[226:229], v[66:69]
	v_mfma_f32_16x16x32_bf16 v[66:69], v[168:171], v[222:225], v[66:69]
	v_mfma_f32_16x16x32_bf16 v[74:77], v[160:163], v[222:225], v[74:77]
	v_mfma_f32_16x16x32_bf16 v[74:77], v[164:167], v[226:229], v[74:77]
	v_mfma_f32_16x16x32_bf16 v[90:93], v[164:167], v[218:221], v[90:93]
	v_mfma_f32_16x16x32_bf16 v[90:93], v[160:163], v[214:217], v[90:93]
	v_mfma_f32_16x16x32_bf16 v[106:109], v[160:163], v[184:187], v[106:109]
	v_mfma_f32_16x16x32_bf16 v[106:109], v[164:167], v[210:213], v[106:109]
	v_mfma_f32_16x16x32_bf16 v[122:125], v[164:167], v[180:183], v[122:125]
	s_barrier
	v_mfma_f32_16x16x32_bf16 v[122:125], v[160:163], v[176:179], v[122:125]
	s_setprio 0
	s_add_i32 s12, s56, s60
	ds_read_b128 v[176:179], v146 offset:49152
	ds_read_b128 v[180:183], v146 offset:50176
	ds_read_b128 v[184:187], v146 offset:51200
	ds_read_b128 v[210:213], v146 offset:52224
	ds_read_b128 v[214:217], v146 offset:53248
	ds_read_b128 v[218:221], v146 offset:54272
	ds_read_b128 v[222:225], v146 offset:55296
	ds_read_b128 v[226:229], v146 offset:56320
	s_mov_b32 m0, s12
	s_nop 0
	global_load_lds_dwordx4 v231, s[30:31]
	s_add_i32 m0, s12, 0x2000
	s_add_u32 s12, s30, 0x100080
	s_addc_u32 s13, s31, 0
	global_load_lds_dwordx4 v188, s[30:31]
	s_add_i32 s30, s61, s60
	s_mov_b32 m0, s30
	s_nop 0
	global_load_lds_dwordx4 v190, s[12:13]
	s_add_i32 m0, s30, 0x2000
	s_nop 0
	global_load_lds_dwordx4 v130, s[12:13]
	s_mov_b32 m0, s68
	s_nop 0
	global_load_lds_dwordx4 v230, s[52:53]
	s_mov_b32 m0, s69
	s_nop 0
	global_load_lds_dwordx4 v189, s[52:53]
	s_waitcnt vmcnt(8)
	s_waitcnt lgkmcnt(0)
	s_barrier
	s_setprio 1
	s_waitcnt lgkmcnt(0)
	v_mfma_f32_16x16x32_bf16 v[62:65], v[140:143], v[176:179], v[62:65]
	v_mfma_f32_16x16x32_bf16 v[62:65], v[148:151], v[180:183], v[62:65]
	v_mfma_f32_16x16x32_bf16 v[46:49], v[148:151], v[210:213], v[46:49]
	v_mfma_f32_16x16x32_bf16 v[46:49], v[140:143], v[184:187], v[46:49]
	v_mfma_f32_16x16x32_bf16 v[30:33], v[140:143], v[214:217], v[30:33]
	v_mfma_f32_16x16x32_bf16 v[30:33], v[148:151], v[218:221], v[30:33]
	v_mfma_f32_16x16x32_bf16 v[14:17], v[148:151], v[226:229], v[14:17]
	v_mfma_f32_16x16x32_bf16 v[14:17], v[140:143], v[222:225], v[14:17]
	v_mfma_f32_16x16x32_bf16 v[6:9], v[152:155], v[222:225], v[6:9]
	v_mfma_f32_16x16x32_bf16 v[6:9], v[156:159], v[226:229], v[6:9]
	v_mfma_f32_16x16x32_bf16 v[22:25], v[156:159], v[218:221], v[22:25]
	v_mfma_f32_16x16x32_bf16 v[22:25], v[152:155], v[214:217], v[22:25]
	v_mfma_f32_16x16x32_bf16 v[38:41], v[152:155], v[184:187], v[38:41]
	v_mfma_f32_16x16x32_bf16 v[38:41], v[156:159], v[210:213], v[38:41]
	v_mfma_f32_16x16x32_bf16 v[54:57], v[156:159], v[180:183], v[54:57]
	v_mfma_f32_16x16x32_bf16 v[54:57], v[152:155], v[176:179], v[54:57]
	v_mfma_f32_16x16x32_bf16 v[50:53], v[168:171], v[176:179], v[50:53]
	v_mfma_f32_16x16x32_bf16 v[50:53], v[172:175], v[180:183], v[50:53]
	v_mfma_f32_16x16x32_bf16 v[34:37], v[172:175], v[210:213], v[34:37]
	v_mfma_f32_16x16x32_bf16 v[34:37], v[168:171], v[184:187], v[34:37]
	v_mfma_f32_16x16x32_bf16 v[18:21], v[168:171], v[214:217], v[18:21]
	v_mfma_f32_16x16x32_bf16 v[18:21], v[172:175], v[218:221], v[18:21]
	v_mfma_f32_16x16x32_bf16 v[2:5], v[172:175], v[226:229], v[2:5]
	v_mfma_f32_16x16x32_bf16 v[2:5], v[168:171], v[222:225], v[2:5]
	v_mfma_f32_16x16x32_bf16 v[10:13], v[160:163], v[222:225], v[10:13]
	v_mfma_f32_16x16x32_bf16 v[10:13], v[164:167], v[226:229], v[10:13]
	v_mfma_f32_16x16x32_bf16 v[26:29], v[164:167], v[218:221], v[26:29]
	v_mfma_f32_16x16x32_bf16 v[26:29], v[160:163], v[214:217], v[26:29]
	v_mfma_f32_16x16x32_bf16 v[42:45], v[160:163], v[184:187], v[42:45]
	v_mfma_f32_16x16x32_bf16 v[42:45], v[164:167], v[210:213], v[42:45]
	v_mfma_f32_16x16x32_bf16 v[58:61], v[164:167], v[180:183], v[58:61]
	s_barrier
	v_mfma_f32_16x16x32_bf16 v[58:61], v[160:163], v[176:179], v[58:61]
	s_setprio 0
	s_add_i32 s47, s47, 2
	s_add_u32 s22, s22, 0x100
	s_addc_u32 s23, s23, 0
	s_add_u32 s33, s33, 0x100
	s_addc_u32 s45, s45, 0
	s_cmp_gt_u32 s47, 61
	s_cbranch_scc0 .LBB0_902
	s_and_b64 vcc, exec, s[42:43]
	s_cbranch_vccz .LBB0_905
	s_barrier

.LBB0_983:
	s_add_u32 s46, s44, 0x100
	s_addc_u32 s47, s45, 0
	s_add_i32 s12, 0, 0x10000
	s_cmpk_eq_i32 s70, 0xa8
	s_cselect_b32 s51, s41, s47
	s_cselect_b32 s50, s40, s46
	s_cselect_b32 s49, s43, s69
	s_cselect_b32 s48, s42, s61
	s_add_i32 s56, 0, 0x14000
	v_add_u32_e32 v142, s12, v193
	v_add_u32_e32 v158, s56, v193
	ds_read_b128 v[130:133], v142
	ds_read_b128 v[134:137], v142 offset:1024
	ds_read_b128 v[138:141], v142 offset:2048
	ds_read_b128 v[142:145], v142 offset:3072
	ds_read_b128 v[146:149], v158
	ds_read_b128 v[150:153], v158 offset:1024
	ds_read_b128 v[154:157], v158 offset:2048
	ds_read_b128 v[158:161], v158 offset:3072
	ds_read_b128 v[162:165], v197
	ds_read_b128 v[166:169], v197 offset:1024
	ds_read_b128 v[170:173], v197 offset:2048
	ds_read_b128 v[174:177], v197 offset:3072
	ds_read_b128 v[178:181], v197 offset:4096
	ds_read_b128 v[182:185], v197 offset:5120
	ds_read_b128 v[186:189], v197 offset:6144
	ds_read_b128 v[220:223], v197 offset:7168
	s_add_i32 m0, s33, 0xc000
	s_nop 0
	global_load_lds_dwordx4 v216, s[44:45]
	s_add_i32 m0, s33, 0xe000
	s_nop 0
	global_load_lds_dwordx4 v218, s[44:45]
	s_waitcnt vmcnt(8)
	s_waitcnt lgkmcnt(0)
	s_barrier
	s_setprio 1
	s_waitcnt lgkmcnt(0)
	v_mfma_f32_16x16x32_bf16 v[126:129], v[130:133], v[162:165], v[126:129]
	v_mfma_f32_16x16x32_bf16 v[126:129], v[134:137], v[166:169], v[126:129]
	v_mfma_f32_16x16x32_bf16 v[110:113], v[134:137], v[174:177], v[110:113]
	v_mfma_f32_16x16x32_bf16 v[110:113], v[130:133], v[170:173], v[110:113]
	v_mfma_f32_16x16x32_bf16 v[98:101], v[130:133], v[178:181], v[98:101]
	v_mfma_f32_16x16x32_bf16 v[98:101], v[134:137], v[182:185], v[98:101]
	v_mfma_f32_16x16x32_bf16 v[82:85], v[134:137], v[220:223], v[82:85]
	v_mfma_f32_16x16x32_bf16 v[82:85], v[130:133], v[186:189], v[82:85]
	v_mfma_f32_16x16x32_bf16 v[74:77], v[138:141], v[186:189], v[74:77]
	v_mfma_f32_16x16x32_bf16 v[74:77], v[142:145], v[220:223], v[74:77]
	v_mfma_f32_16x16x32_bf16 v[90:93], v[142:145], v[182:185], v[90:93]
	v_mfma_f32_16x16x32_bf16 v[90:93], v[138:141], v[178:181], v[90:93]
	v_mfma_f32_16x16x32_bf16 v[106:109], v[138:141], v[170:173], v[106:109]
	v_mfma_f32_16x16x32_bf16 v[106:109], v[142:145], v[174:177], v[106:109]
	v_mfma_f32_16x16x32_bf16 v[122:125], v[142:145], v[166:169], v[122:125]
	v_mfma_f32_16x16x32_bf16 v[122:125], v[138:141], v[162:165], v[122:125]
	v_mfma_f32_16x16x32_bf16 v[114:117], v[154:157], v[162:165], v[114:117]
	v_mfma_f32_16x16x32_bf16 v[114:117], v[158:161], v[166:169], v[114:117]
	v_mfma_f32_16x16x32_bf16 v[94:97], v[158:161], v[174:177], v[94:97]
	v_mfma_f32_16x16x32_bf16 v[94:97], v[154:157], v[170:173], v[94:97]
	v_mfma_f32_16x16x32_bf16 v[78:81], v[154:157], v[178:181], v[78:81]
	v_mfma_f32_16x16x32_bf16 v[78:81], v[158:161], v[182:185], v[78:81]
	v_mfma_f32_16x16x32_bf16 v[66:69], v[158:161], v[220:223], v[66:69]
	v_mfma_f32_16x16x32_bf16 v[66:69], v[154:157], v[186:189], v[66:69]
	v_mfma_f32_16x16x32_bf16 v[70:73], v[146:149], v[186:189], v[70:73]
	v_mfma_f32_16x16x32_bf16 v[70:73], v[150:153], v[220:223], v[70:73]
	v_mfma_f32_16x16x32_bf16 v[86:89], v[150:153], v[182:185], v[86:89]
	v_mfma_f32_16x16x32_bf16 v[86:89], v[146:149], v[178:181], v[86:89]
	v_mfma_f32_16x16x32_bf16 v[102:105], v[146:149], v[170:173], v[102:105]
	v_mfma_f32_16x16x32_bf16 v[102:105], v[150:153], v[174:177], v[102:105]
	v_mfma_f32_16x16x32_bf16 v[118:121], v[150:153], v[166:169], v[118:121]
	s_barrier
	v_mfma_f32_16x16x32_bf16 v[118:121], v[146:149], v[162:165], v[118:121]
	s_setprio 0
	s_add_i32 s12, s12, s29
	ds_read_b128 v[162:165], v197 offset:16384
	ds_read_b128 v[166:169], v197 offset:17408
	ds_read_b128 v[170:173], v197 offset:18432
	ds_read_b128 v[174:177], v197 offset:19456
	ds_read_b128 v[178:181], v197 offset:20480
	ds_read_b128 v[182:185], v197 offset:21504
	ds_read_b128 v[186:189], v197 offset:22528
	ds_read_b128 v[220:223], v197 offset:23552
	s_mov_b32 m0, s12
	s_nop 0
	global_load_lds_dwordx4 v190, s[48:49]
	s_add_i32 m0, s12, 0x2000
	s_add_u32 s12, s48, 0x2b0000
	s_addc_u32 s13, s49, 0
	s_add_i32 s44, s56, s29
	global_load_lds_dwordx4 v214, s[48:49]
	s_mov_b32 m0, s44
	s_nop 0
	global_load_lds_dwordx4 v190, s[12:13]
	s_add_i32 m0, s44, 0x2000
	s_nop 0
	global_load_lds_dwordx4 v214, s[12:13]
	s_mov_b32 m0, s33
	s_nop 0
	global_load_lds_dwordx4 v210, s[50:51]
	s_mov_b32 m0, s57
	s_nop 0
	global_load_lds_dwordx4 v212, s[50:51]
	s_waitcnt vmcnt(8)
	s_waitcnt lgkmcnt(0)
	s_barrier
	s_setprio 1
	s_waitcnt lgkmcnt(0)
	v_mfma_f32_16x16x32_bf16 v[62:65], v[130:133], v[162:165], v[62:65]
	v_mfma_f32_16x16x32_bf16 v[62:65], v[134:137], v[166:169], v[62:65]
	v_mfma_f32_16x16x32_bf16 v[50:53], v[134:137], v[174:177], v[50:53]
	v_mfma_f32_16x16x32_bf16 v[50:53], v[130:133], v[170:173], v[50:53]
	v_mfma_f32_16x16x32_bf16 v[34:37], v[130:133], v[178:181], v[34:37]
	v_mfma_f32_16x16x32_bf16 v[34:37], v[134:137], v[182:185], v[34:37]
	v_mfma_f32_16x16x32_bf16 v[18:21], v[134:137], v[220:223], v[18:21]
	v_mfma_f32_16x16x32_bf16 v[18:21], v[130:133], v[186:189], v[18:21]
	v_mfma_f32_16x16x32_bf16 v[10:13], v[138:141], v[186:189], v[10:13]
	v_mfma_f32_16x16x32_bf16 v[10:13], v[142:145], v[220:223], v[10:13]
	v_mfma_f32_16x16x32_bf16 v[26:29], v[142:145], v[182:185], v[26:29]
	v_mfma_f32_16x16x32_bf16 v[26:29], v[138:141], v[178:181], v[26:29]
	v_mfma_f32_16x16x32_bf16 v[42:45], v[138:141], v[170:173], v[42:45]
	v_mfma_f32_16x16x32_bf16 v[42:45], v[142:145], v[174:177], v[42:45]
	v_mfma_f32_16x16x32_bf16 v[58:61], v[142:145], v[166:169], v[58:61]
	v_mfma_f32_16x16x32_bf16 v[58:61], v[138:141], v[162:165], v[58:61]
	v_mfma_f32_16x16x32_bf16 v[46:49], v[154:157], v[162:165], v[46:49]
	v_mfma_f32_16x16x32_bf16 v[46:49], v[158:161], v[166:169], v[46:49]
	v_mfma_f32_16x16x32_bf16 v[30:33], v[158:161], v[174:177], v[30:33]
	v_mfma_f32_16x16x32_bf16 v[30:33], v[154:157], v[170:173], v[30:33]
	v_mfma_f32_16x16x32_bf16 v[14:17], v[154:157], v[178:181], v[14:17]
	v_mfma_f32_16x16x32_bf16 v[14:17], v[158:161], v[182:185], v[14:17]
	v_mfma_f32_16x16x32_bf16 v[2:5], v[158:161], v[220:223], v[2:5]
	v_mfma_f32_16x16x32_bf16 v[2:5], v[154:157], v[186:189], v[2:5]
	v_mfma_f32_16x16x32_bf16 v[6:9], v[146:149], v[186:189], v[6:9]
	v_mfma_f32_16x16x32_bf16 v[6:9], v[150:153], v[220:223], v[6:9]
	v_mfma_f32_16x16x32_bf16 v[22:25], v[150:153], v[182:185], v[22:25]
	v_mfma_f32_16x16x32_bf16 v[22:25], v[146:149], v[178:181], v[22:25]
	v_mfma_f32_16x16x32_bf16 v[38:41], v[146:149], v[170:173], v[38:41]
	v_mfma_f32_16x16x32_bf16 v[38:41], v[150:153], v[174:177], v[38:41]
	v_mfma_f32_16x16x32_bf16 v[54:57], v[150:153], v[166:169], v[54:57]
	s_barrier
	v_mfma_f32_16x16x32_bf16 v[54:57], v[146:149], v[162:165], v[54:57]
	s_setprio 0
	s_add_i32 s44, 0, 0x18000
	s_add_i32 s45, 0, 0x1c000
	s_add_u32 s12, s50, 0x2b0000
	s_addc_u32 s13, s51, 0
	v_add_u32_e32 v142, s44, v193
	v_add_u32_e32 v158, s45, v193
	ds_read_b128 v[130:133], v142
	ds_read_b128 v[134:137], v142 offset:1024
	ds_read_b128 v[138:141], v142 offset:2048
	ds_read_b128 v[142:145], v142 offset:3072
	ds_read_b128 v[146:149], v158
	ds_read_b128 v[150:153], v158 offset:1024
	ds_read_b128 v[154:157], v158 offset:2048
	ds_read_b128 v[158:161], v158 offset:3072
	ds_read_b128 v[162:165], v197 offset:32768
	ds_read_b128 v[166:169], v197 offset:33792
	ds_read_b128 v[170:173], v197 offset:34816
	ds_read_b128 v[174:177], v197 offset:35840
	ds_read_b128 v[178:181], v197 offset:36864
	ds_read_b128 v[182:185], v197 offset:37888
	ds_read_b128 v[186:189], v197 offset:38912
	ds_read_b128 v[220:223], v197 offset:39936
	s_mov_b32 m0, s58
	s_nop 0
	global_load_lds_dwordx4 v210, s[12:13]
	s_mov_b32 m0, s59
	s_nop 0
	global_load_lds_dwordx4 v212, s[12:13]
	s_waitcnt vmcnt(8)
	s_waitcnt lgkmcnt(0)
	s_barrier
	s_setprio 1
	s_waitcnt lgkmcnt(0)
	v_mfma_f32_16x16x32_bf16 v[126:129], v[130:133], v[162:165], v[126:129]
	v_mfma_f32_16x16x32_bf16 v[126:129], v[134:137], v[166:169], v[126:129]
	v_mfma_f32_16x16x32_bf16 v[110:113], v[134:137], v[174:177], v[110:113]
	v_mfma_f32_16x16x32_bf16 v[110:113], v[130:133], v[170:173], v[110:113]
	v_mfma_f32_16x16x32_bf16 v[98:101], v[130:133], v[178:181], v[98:101]
	v_mfma_f32_16x16x32_bf16 v[98:101], v[134:137], v[182:185], v[98:101]
	v_mfma_f32_16x16x32_bf16 v[82:85], v[134:137], v[220:223], v[82:85]
	v_mfma_f32_16x16x32_bf16 v[82:85], v[130:133], v[186:189], v[82:85]
	v_mfma_f32_16x16x32_bf16 v[74:77], v[138:141], v[186:189], v[74:77]
	v_mfma_f32_16x16x32_bf16 v[74:77], v[142:145], v[220:223], v[74:77]
	v_mfma_f32_16x16x32_bf16 v[90:93], v[142:145], v[182:185], v[90:93]
	v_mfma_f32_16x16x32_bf16 v[90:93], v[138:141], v[178:181], v[90:93]
	v_mfma_f32_16x16x32_bf16 v[106:109], v[138:141], v[170:173], v[106:109]
	v_mfma_f32_16x16x32_bf16 v[106:109], v[142:145], v[174:177], v[106:109]
	v_mfma_f32_16x16x32_bf16 v[122:125], v[142:145], v[166:169], v[122:125]
	v_mfma_f32_16x16x32_bf16 v[122:125], v[138:141], v[162:165], v[122:125]
	v_mfma_f32_16x16x32_bf16 v[114:117], v[154:157], v[162:165], v[114:117]
	v_mfma_f32_16x16x32_bf16 v[114:117], v[158:161], v[166:169], v[114:117]
	v_mfma_f32_16x16x32_bf16 v[94:97], v[158:161], v[174:177], v[94:97]
	v_mfma_f32_16x16x32_bf16 v[94:97], v[154:157], v[170:173], v[94:97]
	v_mfma_f32_16x16x32_bf16 v[78:81], v[154:157], v[178:181], v[78:81]
	v_mfma_f32_16x16x32_bf16 v[78:81], v[158:161], v[182:185], v[78:81]
	v_mfma_f32_16x16x32_bf16 v[66:69], v[158:161], v[220:223], v[66:69]
	v_mfma_f32_16x16x32_bf16 v[66:69], v[154:157], v[186:189], v[66:69]
	v_mfma_f32_16x16x32_bf16 v[70:73], v[146:149], v[186:189], v[70:73]
	v_mfma_f32_16x16x32_bf16 v[70:73], v[150:153], v[220:223], v[70:73]
	v_mfma_f32_16x16x32_bf16 v[86:89], v[150:153], v[182:185], v[86:89]
	v_mfma_f32_16x16x32_bf16 v[86:89], v[146:149], v[178:181], v[86:89]
	v_mfma_f32_16x16x32_bf16 v[102:105], v[146:149], v[170:173], v[102:105]
	v_mfma_f32_16x16x32_bf16 v[102:105], v[150:153], v[174:177], v[102:105]
	v_mfma_f32_16x16x32_bf16 v[118:121], v[150:153], v[166:169], v[118:121]
	s_barrier
	v_mfma_f32_16x16x32_bf16 v[118:121], v[146:149], v[162:165], v[118:121]
	s_setprio 0
	s_add_i32 s12, s44, s29
	ds_read_b128 v[162:165], v197 offset:49152
	ds_read_b128 v[166:169], v197 offset:50176
	ds_read_b128 v[170:173], v197 offset:51200
	ds_read_b128 v[174:177], v197 offset:52224
	ds_read_b128 v[178:181], v197 offset:53248
	ds_read_b128 v[182:185], v197 offset:54272
	ds_read_b128 v[186:189], v197 offset:55296
	ds_read_b128 v[220:223], v197 offset:56320
	s_mov_b32 m0, s12
	s_nop 0
	global_load_lds_dwordx4 v224, s[48:49]
	s_add_i32 m0, s12, 0x2000
	s_add_u32 s12, s48, 0x2b0080
	s_addc_u32 s13, s49, 0
	s_add_i32 s44, s45, s29
	global_load_lds_dwordx4 v227, s[48:49]
	s_mov_b32 m0, s44
	s_nop 0
	global_load_lds_dwordx4 v190, s[12:13]
	s_add_i32 m0, s44, 0x2000
	s_nop 0
	global_load_lds_dwordx4 v214, s[12:13]
	s_mov_b32 m0, s60
	s_nop 0
	global_load_lds_dwordx4 v225, s[50:51]
	s_mov_b32 m0, s62
	s_nop 0
	global_load_lds_dwordx4 v226, s[50:51]
	s_waitcnt vmcnt(8)
	s_waitcnt lgkmcnt(0)
	s_barrier
	s_setprio 1
	s_waitcnt lgkmcnt(0)
	v_mfma_f32_16x16x32_bf16 v[62:65], v[130:133], v[162:165], v[62:65]
	v_mfma_f32_16x16x32_bf16 v[62:65], v[134:137], v[166:169], v[62:65]
	v_mfma_f32_16x16x32_bf16 v[50:53], v[134:137], v[174:177], v[50:53]
	v_mfma_f32_16x16x32_bf16 v[50:53], v[130:133], v[170:173], v[50:53]
	v_mfma_f32_16x16x32_bf16 v[34:37], v[130:133], v[178:181], v[34:37]
	v_mfma_f32_16x16x32_bf16 v[34:37], v[134:137], v[182:185], v[34:37]
	v_mfma_f32_16x16x32_bf16 v[18:21], v[134:137], v[220:223], v[18:21]
	v_mfma_f32_16x16x32_bf16 v[18:21], v[130:133], v[186:189], v[18:21]
	v_mfma_f32_16x16x32_bf16 v[10:13], v[138:141], v[186:189], v[10:13]
	v_mfma_f32_16x16x32_bf16 v[10:13], v[142:145], v[220:223], v[10:13]
	v_mfma_f32_16x16x32_bf16 v[26:29], v[142:145], v[182:185], v[26:29]
	v_mfma_f32_16x16x32_bf16 v[26:29], v[138:141], v[178:181], v[26:29]
	v_mfma_f32_16x16x32_bf16 v[42:45], v[138:141], v[170:173], v[42:45]
	v_mfma_f32_16x16x32_bf16 v[42:45], v[142:145], v[174:177], v[42:45]
	v_mfma_f32_16x16x32_bf16 v[58:61], v[142:145], v[166:169], v[58:61]
	v_mfma_f32_16x16x32_bf16 v[58:61], v[138:141], v[162:165], v[58:61]
	v_mfma_f32_16x16x32_bf16 v[46:49], v[154:157], v[162:165], v[46:49]
	v_mfma_f32_16x16x32_bf16 v[46:49], v[158:161], v[166:169], v[46:49]
	v_mfma_f32_16x16x32_bf16 v[30:33], v[158:161], v[174:177], v[30:33]
	v_mfma_f32_16x16x32_bf16 v[30:33], v[154:157], v[170:173], v[30:33]
	v_mfma_f32_16x16x32_bf16 v[14:17], v[154:157], v[178:181], v[14:17]
	v_mfma_f32_16x16x32_bf16 v[14:17], v[158:161], v[182:185], v[14:17]
	v_mfma_f32_16x16x32_bf16 v[2:5], v[158:161], v[220:223], v[2:5]
	v_mfma_f32_16x16x32_bf16 v[2:5], v[154:157], v[186:189], v[2:5]
	v_mfma_f32_16x16x32_bf16 v[6:9], v[146:149], v[186:189], v[6:9]
	v_mfma_f32_16x16x32_bf16 v[6:9], v[150:153], v[220:223], v[6:9]
	v_mfma_f32_16x16x32_bf16 v[22:25], v[150:153], v[182:185], v[22:25]
	v_mfma_f32_16x16x32_bf16 v[22:25], v[146:149], v[178:181], v[22:25]
	v_mfma_f32_16x16x32_bf16 v[38:41], v[146:149], v[170:173], v[38:41]
	v_mfma_f32_16x16x32_bf16 v[38:41], v[150:153], v[174:177], v[38:41]
	v_mfma_f32_16x16x32_bf16 v[54:57], v[150:153], v[166:169], v[54:57]
	s_barrier
	v_mfma_f32_16x16x32_bf16 v[54:57], v[146:149], v[162:165], v[54:57]
	s_setprio 0
	s_add_i32 s70, s70, 2
	s_add_u32 s61, s61, 0x100
	s_addc_u32 s69, s69, 0
	s_cmpk_gt_u32 s70, 0xa9
	s_mov_b64 s[44:45], s[46:47]
	s_cbranch_scc0 .LBB0_983
	s_and_b64 vcc, exec, s[30:31]
	s_cbranch_vccz .LBB0_986
	s_barrier
